# peeled first K-iteration: second load segment also stops waiting for epilogue stores; phase prologue drains its tile loads once
# speedup vs baseline: 1.0043x; 1.0016x over previous
.LBB0_23:
	s_add_u32 s7, s70, 0xa140000
	s_addc_u32 s8, s71, 0
	s_cmp_lt_i32 s1, 11
	s_cselect_b32 s15, s8, 0
	s_cselect_b32 s14, s7, 0
	s_lshl_b32 s6, s6, 5
	s_and_b32 s8, s6, 0x60
	s_add_i32 m0, s41, 0x18000
	v_lshl_add_u64 v[6:7], v[6:7], 0, s[54:55]
	s_lshl_b32 s1, s0, 13
	s_lshl_b32 s9, s8, 7
	s_waitcnt vmcnt(2)
	s_barrier
	global_load_lds_dwordx4 v[6:7], off
	v_lshl_add_u64 v[4:5], v[4:5], 0, s[54:55]
	s_add_i32 m0, s41, 0x1a000
	s_add_i32 s47, s41, 0x8000
	s_add_i32 s48, s41, 0xa000
	global_load_lds_dwordx4 v[4:5], off
	v_lshl_add_u64 v[0:1], v[0:1], 0, s[54:55]
	s_mov_b32 m0, s47
	s_add_u32 s6, s28, 0x160080
	global_load_lds_dwordx4 v[0:1], off
	v_lshl_add_u64 v[0:1], v[2:3], 0, s[54:55]
	s_mov_b32 m0, s48
	s_addc_u32 s7, s29, 0
	global_load_lds_dwordx4 v[0:1], off
	s_add_i32 m0, s41, 0x1c000
	v_lshl_add_u64 v[0:1], s[6:7], 0, v[198:199]
	global_load_lds_dwordx4 v[0:1], off
	v_lshl_add_u64 v[0:1], s[6:7], 0, v[212:213]
	s_add_i32 m0, s41, 0x1e000
	s_waitcnt lgkmcnt(0)
	s_ashr_i32 s50, s27, 31
	global_load_lds_dwordx4 v[0:1], off
	v_bfe_u32 v1, v8, 4, 2
	v_and_b32_e32 v0, 15, v8
	v_lshlrev_b32_e32 v2, 4, v1
	v_lshl_or_b32 v204, s0, 6, v0
	v_lshl_or_b32 v0, v0, 6, v2
	v_lshlrev_b32_e32 v2, 2, v8
	v_and_b32_e32 v2, 32, v2
	v_lshl_or_b32 v252, v1, 2, s8
	s_movk_i32 s8, 0x1600
	v_bitop3_b32 v3, v0, s1, v2 bitop3:0xde
	v_bitop3_b32 v251, s9, v0, v2 bitop3:0xf6
	v_cmp_eq_u32_e64 s[6:7], 0, v1
	v_lshrrev_b32_e32 v1, 1, v9
	v_mul_lo_u32 v0, v11, s8
	s_mov_b32 s9, 0x16000
	v_mad_u64_u32 v[0:1], s[0:1], v1, s9, v[0:1]
	v_or_b32_e32 v0, v0, v10
	s_cmpk_lt_u32 s10, 0x100
	v_add_lshl_u32 v0, v0, v12, 1
	v_mov_b32_e32 v1, v199
	s_mov_b64 s[10:11], 0x160080
	v_lshl_add_u64 v[214:215], v[0:1], 0, s[10:11]
	v_lshrrev_b32_e32 v1, 1, v13
	v_mul_lo_u32 v0, v15, s8
	v_mad_u64_u32 v[0:1], s[0:1], v1, s9, v[0:1]
	s_waitcnt vmcnt(0)
	v_or_b32_e32 v0, v0, v14
	s_cselect_b64 s[16:17], -1, 0
	s_cmp_lg_u64 s[14:15], 0
	v_add_lshl_u32 v0, v0, v16, 1
	v_mov_b32_e32 v1, v199
	s_mov_b32 s49, 0
	s_cselect_b64 s[18:19], -1, 0
	v_lshl_add_u64 v[216:217], v[0:1], 0, s[10:11]
	v_add_u32_e32 v253, 0, v3
	s_barrier
	s_branch .LBB0_26

.LBB0_36:
	s_add_u32 s34, s28, 0x100
	s_addc_u32 s35, s29, 0
	s_mov_b32 s79, -2
	s_waitcnt lgkmcnt(0)
	s_add_u32 s10, s24, 0x100
	s_addc_u32 s11, s25, 0
	s_add_i32 s0, 0, 0x10000
	s_cmpk_eq_i32 s79, 0x54
	s_cselect_b32 s31, s21, s11
	s_cselect_b32 s30, s20, s10
	s_cselect_b32 s29, s23, s35
	s_cselect_b32 s28, s22, s34
	s_add_i32 s59, 0, 0x14000
	v_add_u32_e32 v140, s0, v251
	v_add_u32_e32 v156, s59, v251
	ds_read_b128 v[124:127], v140
	ds_read_b128 v[128:131], v140 offset:1024
	ds_read_b128 v[132:135], v140 offset:2048
	ds_read_b128 v[140:143], v140 offset:3072
	ds_read_b128 v[144:147], v156
	ds_read_b128 v[148:151], v156 offset:1024
	ds_read_b128 v[152:155], v156 offset:2048
	ds_read_b128 v[156:159], v156 offset:3072
	v_lshl_add_u64 v[192:193], s[24:25], 0, v[214:215]
	s_add_i32 m0, s41, 0xc000
	ds_read_b128 v[160:163], v253
	ds_read_b128 v[164:167], v253 offset:1024
	ds_read_b128 v[168:171], v253 offset:2048
	ds_read_b128 v[172:175], v253 offset:3072
	ds_read_b128 v[176:179], v253 offset:4096
	ds_read_b128 v[180:183], v253 offset:5120
	ds_read_b128 v[184:187], v253 offset:6144
	ds_read_b128 v[188:191], v253 offset:7168
	global_load_lds_dwordx4 v[192:193], off
	v_lshl_add_u64 v[192:193], s[24:25], 0, v[216:217]
	s_add_i32 m0, s41, 0xe000
	s_nop 0
	global_load_lds_dwordx4 v[192:193], off
	s_waitcnt vmcnt(63)
	s_waitcnt lgkmcnt(0)
	s_barrier
	s_setprio 1
	s_waitcnt lgkmcnt(0)
	v_mfma_f32_16x16x32_bf16 v[136:139], v[124:127], v[160:163], 0
	v_mfma_f32_16x16x32_bf16 v[120:123], v[132:135], v[160:163], 0
	v_mfma_f32_16x16x32_bf16 v[116:119], v[124:127], v[168:171], 0
	v_mfma_f32_16x16x32_bf16 v[104:107], v[132:135], v[168:171], 0
	v_mfma_f32_16x16x32_bf16 v[100:103], v[124:127], v[176:179], 0
	v_mfma_f32_16x16x32_bf16 v[88:91], v[132:135], v[176:179], 0
	v_mfma_f32_16x16x32_bf16 v[84:87], v[124:127], v[184:187], 0
	v_mfma_f32_16x16x32_bf16 v[72:75], v[132:135], v[184:187], 0
	v_mfma_f32_16x16x32_bf16 v[136:139], v[128:131], v[164:167], v[136:139]
	v_mfma_f32_16x16x32_bf16 v[120:123], v[140:143], v[164:167], v[120:123]
	v_mfma_f32_16x16x32_bf16 v[116:119], v[128:131], v[172:175], v[116:119]
	v_mfma_f32_16x16x32_bf16 v[104:107], v[140:143], v[172:175], v[104:107]
	v_mfma_f32_16x16x32_bf16 v[100:103], v[128:131], v[180:183], v[100:103]
	v_mfma_f32_16x16x32_bf16 v[88:91], v[140:143], v[180:183], v[88:91]
	v_mfma_f32_16x16x32_bf16 v[84:87], v[128:131], v[188:191], v[84:87]
	v_mfma_f32_16x16x32_bf16 v[72:75], v[140:143], v[188:191], v[72:75]
	s_setprio 0
	s_setprio 1
	v_mfma_f32_16x16x32_bf16 v[112:115], v[144:147], v[160:163], 0
	v_mfma_f32_16x16x32_bf16 v[108:111], v[152:155], v[160:163], 0
	v_mfma_f32_16x16x32_bf16 v[96:99], v[144:147], v[168:171], 0
	v_mfma_f32_16x16x32_bf16 v[92:95], v[152:155], v[168:171], 0
	v_mfma_f32_16x16x32_bf16 v[80:83], v[144:147], v[176:179], 0
	v_mfma_f32_16x16x32_bf16 v[76:79], v[152:155], v[176:179], 0
	v_mfma_f32_16x16x32_bf16 v[68:71], v[144:147], v[184:187], 0
	v_mfma_f32_16x16x32_bf16 v[64:67], v[152:155], v[184:187], 0
	v_mfma_f32_16x16x32_bf16 v[112:115], v[148:151], v[164:167], v[112:115]
	v_mfma_f32_16x16x32_bf16 v[108:111], v[156:159], v[164:167], v[108:111]
	v_mfma_f32_16x16x32_bf16 v[96:99], v[148:151], v[172:175], v[96:99]
	v_mfma_f32_16x16x32_bf16 v[92:95], v[156:159], v[172:175], v[92:95]
	v_mfma_f32_16x16x32_bf16 v[80:83], v[148:151], v[180:183], v[80:83]
	v_mfma_f32_16x16x32_bf16 v[76:79], v[156:159], v[180:183], v[76:79]
	v_mfma_f32_16x16x32_bf16 v[68:71], v[148:151], v[188:191], v[68:71]
	v_mfma_f32_16x16x32_bf16 v[64:67], v[156:159], v[188:191], v[64:67]
	s_setprio 0
	s_barrier
	s_add_i32 s0, s0, s40
	v_lshl_add_u64 v[192:193], s[28:29], 0, v[198:199]
	s_mov_b32 m0, s0
	ds_read_b128 v[160:163], v253 offset:16384
	ds_read_b128 v[164:167], v253 offset:17408
	ds_read_b128 v[168:171], v253 offset:18432
	ds_read_b128 v[172:175], v253 offset:19456
	ds_read_b128 v[176:179], v253 offset:20480
	ds_read_b128 v[180:183], v253 offset:21504
	ds_read_b128 v[184:187], v253 offset:22528
	ds_read_b128 v[188:191], v253 offset:23552
	global_load_lds_dwordx4 v[192:193], off
	s_add_i32 m0, s0, 0x2000
	s_add_u32 s0, s28, 0x160000
	v_lshl_add_u64 v[194:195], s[28:29], 0, v[212:213]
	s_addc_u32 s1, s29, 0
	s_add_i32 s24, s59, s40
	global_load_lds_dwordx4 v[194:195], off
	v_lshl_add_u64 v[196:197], s[0:1], 0, v[198:199]
	s_mov_b32 m0, s24
	v_lshl_add_u64 v[218:219], s[30:31], 0, v[212:213]
	global_load_lds_dwordx4 v[196:197], off
	v_lshl_add_u64 v[196:197], s[0:1], 0, v[212:213]
	s_add_i32 m0, s24, 0x2000
	s_nop 0
	global_load_lds_dwordx4 v[196:197], off
	v_lshl_add_u64 v[196:197], s[30:31], 0, v[198:199]
	s_mov_b32 m0, s41
	s_nop 0
	global_load_lds_dwordx4 v[196:197], off
	s_mov_b32 m0, s42
	s_nop 0
	global_load_lds_dwordx4 v[218:219], off
	s_waitcnt vmcnt(63)
	s_waitcnt lgkmcnt(0)
	s_barrier
	s_setprio 1
	s_waitcnt lgkmcnt(0)
	v_mfma_f32_16x16x32_bf16 v[60:63], v[124:127], v[160:163], 0
	v_mfma_f32_16x16x32_bf16 v[56:59], v[132:135], v[160:163], 0
	v_mfma_f32_16x16x32_bf16 v[52:55], v[124:127], v[168:171], 0
	v_mfma_f32_16x16x32_bf16 v[40:43], v[132:135], v[168:171], 0
	v_mfma_f32_16x16x32_bf16 v[36:39], v[124:127], v[176:179], 0
	v_mfma_f32_16x16x32_bf16 v[24:27], v[132:135], v[176:179], 0
	v_mfma_f32_16x16x32_bf16 v[20:23], v[124:127], v[184:187], 0
	v_mfma_f32_16x16x32_bf16 v[8:11], v[132:135], v[184:187], 0
	v_mfma_f32_16x16x32_bf16 v[60:63], v[128:131], v[164:167], v[60:63]
	v_mfma_f32_16x16x32_bf16 v[56:59], v[140:143], v[164:167], v[56:59]
	v_mfma_f32_16x16x32_bf16 v[52:55], v[128:131], v[172:175], v[52:55]
	v_mfma_f32_16x16x32_bf16 v[40:43], v[140:143], v[172:175], v[40:43]
	v_mfma_f32_16x16x32_bf16 v[36:39], v[128:131], v[180:183], v[36:39]
	v_mfma_f32_16x16x32_bf16 v[24:27], v[140:143], v[180:183], v[24:27]
	v_mfma_f32_16x16x32_bf16 v[20:23], v[128:131], v[188:191], v[20:23]
	v_mfma_f32_16x16x32_bf16 v[8:11], v[140:143], v[188:191], v[8:11]
	s_setprio 0
	s_setprio 1
	v_mfma_f32_16x16x32_bf16 v[48:51], v[144:147], v[160:163], 0
	v_mfma_f32_16x16x32_bf16 v[44:47], v[152:155], v[160:163], 0
	v_mfma_f32_16x16x32_bf16 v[32:35], v[144:147], v[168:171], 0
	v_mfma_f32_16x16x32_bf16 v[28:31], v[152:155], v[168:171], 0
	v_mfma_f32_16x16x32_bf16 v[16:19], v[144:147], v[176:179], 0
	v_mfma_f32_16x16x32_bf16 v[12:15], v[152:155], v[176:179], 0
	v_mfma_f32_16x16x32_bf16 v[4:7], v[144:147], v[184:187], 0
	v_mfma_f32_16x16x32_bf16 v[0:3], v[152:155], v[184:187], 0
	v_mfma_f32_16x16x32_bf16 v[48:51], v[148:151], v[164:167], v[48:51]
	v_mfma_f32_16x16x32_bf16 v[44:47], v[156:159], v[164:167], v[44:47]
	v_mfma_f32_16x16x32_bf16 v[32:35], v[148:151], v[172:175], v[32:35]
	v_mfma_f32_16x16x32_bf16 v[28:31], v[156:159], v[172:175], v[28:31]
	v_mfma_f32_16x16x32_bf16 v[16:19], v[148:151], v[180:183], v[16:19]
	v_mfma_f32_16x16x32_bf16 v[12:15], v[156:159], v[180:183], v[12:15]
	v_mfma_f32_16x16x32_bf16 v[4:7], v[148:151], v[188:191], v[4:7]
	v_mfma_f32_16x16x32_bf16 v[0:3], v[156:159], v[188:191], v[0:3]
	s_setprio 0
	s_barrier
	s_add_i32 s24, 0, 0x18000
	s_add_i32 s25, 0, 0x1c000
	v_add_u32_e32 v140, s24, v251
	v_add_u32_e32 v156, s25, v251
	ds_read_b128 v[124:127], v140
	ds_read_b128 v[128:131], v140 offset:1024
	ds_read_b128 v[132:135], v140 offset:2048
	ds_read_b128 v[140:143], v140 offset:3072
	ds_read_b128 v[144:147], v156
	ds_read_b128 v[148:151], v156 offset:1024
	ds_read_b128 v[152:155], v156 offset:2048
	ds_read_b128 v[156:159], v156 offset:3072
	s_add_u32 s0, s30, 0x160000
	s_addc_u32 s1, s31, 0
	s_mov_b32 m0, s43
	v_lshl_add_u64 v[220:221], s[0:1], 0, v[198:199]
	ds_read_b128 v[160:163], v253 offset:32768
	ds_read_b128 v[164:167], v253 offset:33792
	ds_read_b128 v[168:171], v253 offset:34816
	ds_read_b128 v[172:175], v253 offset:35840
	ds_read_b128 v[176:179], v253 offset:36864
	ds_read_b128 v[180:183], v253 offset:37888
	ds_read_b128 v[184:187], v253 offset:38912
	ds_read_b128 v[188:191], v253 offset:39936
	global_load_lds_dwordx4 v[220:221], off
	v_lshl_add_u64 v[220:221], s[0:1], 0, v[212:213]
	s_mov_b32 m0, s46
	s_nop 0
	global_load_lds_dwordx4 v[220:221], off
	s_waitcnt vmcnt(8)
	s_waitcnt lgkmcnt(0)
	s_barrier
	s_setprio 1
	s_waitcnt lgkmcnt(0)
	v_mfma_f32_16x16x32_bf16 v[136:139], v[124:127], v[160:163], v[136:139]
	v_mfma_f32_16x16x32_bf16 v[120:123], v[132:135], v[160:163], v[120:123]
	v_mfma_f32_16x16x32_bf16 v[116:119], v[124:127], v[168:171], v[116:119]
	v_mfma_f32_16x16x32_bf16 v[104:107], v[132:135], v[168:171], v[104:107]
	v_mfma_f32_16x16x32_bf16 v[100:103], v[124:127], v[176:179], v[100:103]
	v_mfma_f32_16x16x32_bf16 v[88:91], v[132:135], v[176:179], v[88:91]
	v_mfma_f32_16x16x32_bf16 v[84:87], v[124:127], v[184:187], v[84:87]
	v_mfma_f32_16x16x32_bf16 v[72:75], v[132:135], v[184:187], v[72:75]
	v_mfma_f32_16x16x32_bf16 v[136:139], v[128:131], v[164:167], v[136:139]
	v_mfma_f32_16x16x32_bf16 v[120:123], v[140:143], v[164:167], v[120:123]
	v_mfma_f32_16x16x32_bf16 v[116:119], v[128:131], v[172:175], v[116:119]
	v_mfma_f32_16x16x32_bf16 v[104:107], v[140:143], v[172:175], v[104:107]
	v_mfma_f32_16x16x32_bf16 v[100:103], v[128:131], v[180:183], v[100:103]
	v_mfma_f32_16x16x32_bf16 v[88:91], v[140:143], v[180:183], v[88:91]
	v_mfma_f32_16x16x32_bf16 v[84:87], v[128:131], v[188:191], v[84:87]
	v_mfma_f32_16x16x32_bf16 v[72:75], v[140:143], v[188:191], v[72:75]
	s_setprio 0
	s_setprio 1
	v_mfma_f32_16x16x32_bf16 v[112:115], v[144:147], v[160:163], v[112:115]
	v_mfma_f32_16x16x32_bf16 v[108:111], v[152:155], v[160:163], v[108:111]
	v_mfma_f32_16x16x32_bf16 v[96:99], v[144:147], v[168:171], v[96:99]
	v_mfma_f32_16x16x32_bf16 v[92:95], v[152:155], v[168:171], v[92:95]
	v_mfma_f32_16x16x32_bf16 v[80:83], v[144:147], v[176:179], v[80:83]
	v_mfma_f32_16x16x32_bf16 v[76:79], v[152:155], v[176:179], v[76:79]
	v_mfma_f32_16x16x32_bf16 v[68:71], v[144:147], v[184:187], v[68:71]
	v_mfma_f32_16x16x32_bf16 v[64:67], v[152:155], v[184:187], v[64:67]
	v_mfma_f32_16x16x32_bf16 v[112:115], v[148:151], v[164:167], v[112:115]
	v_mfma_f32_16x16x32_bf16 v[108:111], v[156:159], v[164:167], v[108:111]
	v_mfma_f32_16x16x32_bf16 v[96:99], v[148:151], v[172:175], v[96:99]
	v_mfma_f32_16x16x32_bf16 v[92:95], v[156:159], v[172:175], v[92:95]
	v_mfma_f32_16x16x32_bf16 v[80:83], v[148:151], v[180:183], v[80:83]
	v_mfma_f32_16x16x32_bf16 v[76:79], v[156:159], v[180:183], v[76:79]
	v_mfma_f32_16x16x32_bf16 v[68:71], v[148:151], v[188:191], v[68:71]
	v_mfma_f32_16x16x32_bf16 v[64:67], v[156:159], v[188:191], v[64:67]
	s_setprio 0
	s_barrier
	s_add_i32 s0, s24, s40
	v_lshl_add_u64 v[192:193], v[192:193], 0, s[54:55]
	s_mov_b32 m0, s0
	ds_read_b128 v[160:163], v253 offset:49152
	ds_read_b128 v[164:167], v253 offset:50176
	ds_read_b128 v[168:171], v253 offset:51200
	ds_read_b128 v[172:175], v253 offset:52224
	ds_read_b128 v[176:179], v253 offset:53248
	ds_read_b128 v[180:183], v253 offset:54272
	ds_read_b128 v[184:187], v253 offset:55296
	ds_read_b128 v[188:191], v253 offset:56320
	global_load_lds_dwordx4 v[192:193], off
	s_add_i32 m0, s0, 0x2000
	s_add_u32 s0, s28, 0x160080
	v_lshl_add_u64 v[192:193], v[194:195], 0, s[54:55]
	s_addc_u32 s1, s29, 0
	s_add_i32 s24, s25, s40
	global_load_lds_dwordx4 v[192:193], off
	v_lshl_add_u64 v[192:193], s[0:1], 0, v[198:199]
	s_mov_b32 m0, s24
	s_nop 0
	global_load_lds_dwordx4 v[192:193], off
	v_lshl_add_u64 v[192:193], s[0:1], 0, v[212:213]
	s_add_i32 m0, s24, 0x2000
	s_nop 0
	global_load_lds_dwordx4 v[192:193], off
	v_lshl_add_u64 v[192:193], v[196:197], 0, s[54:55]
	s_mov_b32 m0, s47
	s_nop 0
	global_load_lds_dwordx4 v[192:193], off
	v_lshl_add_u64 v[192:193], v[218:219], 0, s[54:55]
	s_mov_b32 m0, s48
	s_nop 0
	global_load_lds_dwordx4 v[192:193], off
	s_waitcnt vmcnt(8)
	s_waitcnt lgkmcnt(0)
	s_barrier
	s_setprio 1
	s_waitcnt lgkmcnt(0)
	v_mfma_f32_16x16x32_bf16 v[60:63], v[124:127], v[160:163], v[60:63]
	v_mfma_f32_16x16x32_bf16 v[56:59], v[132:135], v[160:163], v[56:59]
	v_mfma_f32_16x16x32_bf16 v[52:55], v[124:127], v[168:171], v[52:55]
	v_mfma_f32_16x16x32_bf16 v[40:43], v[132:135], v[168:171], v[40:43]
	v_mfma_f32_16x16x32_bf16 v[36:39], v[124:127], v[176:179], v[36:39]
	v_mfma_f32_16x16x32_bf16 v[24:27], v[132:135], v[176:179], v[24:27]
	v_mfma_f32_16x16x32_bf16 v[20:23], v[124:127], v[184:187], v[20:23]
	v_mfma_f32_16x16x32_bf16 v[8:11], v[132:135], v[184:187], v[8:11]
	v_mfma_f32_16x16x32_bf16 v[60:63], v[128:131], v[164:167], v[60:63]
	v_mfma_f32_16x16x32_bf16 v[56:59], v[140:143], v[164:167], v[56:59]
	v_mfma_f32_16x16x32_bf16 v[52:55], v[128:131], v[172:175], v[52:55]
	v_mfma_f32_16x16x32_bf16 v[40:43], v[140:143], v[172:175], v[40:43]
	v_mfma_f32_16x16x32_bf16 v[36:39], v[128:131], v[180:183], v[36:39]
	v_mfma_f32_16x16x32_bf16 v[24:27], v[140:143], v[180:183], v[24:27]
	v_mfma_f32_16x16x32_bf16 v[20:23], v[128:131], v[188:191], v[20:23]
	v_mfma_f32_16x16x32_bf16 v[8:11], v[140:143], v[188:191], v[8:11]
	s_setprio 0
	s_setprio 1
	v_mfma_f32_16x16x32_bf16 v[48:51], v[144:147], v[160:163], v[48:51]
	v_mfma_f32_16x16x32_bf16 v[44:47], v[152:155], v[160:163], v[44:47]
	v_mfma_f32_16x16x32_bf16 v[32:35], v[144:147], v[168:171], v[32:35]
	v_mfma_f32_16x16x32_bf16 v[28:31], v[152:155], v[168:171], v[28:31]
	v_mfma_f32_16x16x32_bf16 v[16:19], v[144:147], v[176:179], v[16:19]
	v_mfma_f32_16x16x32_bf16 v[12:15], v[152:155], v[176:179], v[12:15]
	v_mfma_f32_16x16x32_bf16 v[4:7], v[144:147], v[184:187], v[4:7]
	v_mfma_f32_16x16x32_bf16 v[0:3], v[152:155], v[184:187], v[0:3]
	v_mfma_f32_16x16x32_bf16 v[48:51], v[148:151], v[164:167], v[48:51]
	v_mfma_f32_16x16x32_bf16 v[44:47], v[156:159], v[164:167], v[44:47]
	v_mfma_f32_16x16x32_bf16 v[32:35], v[148:151], v[172:175], v[32:35]
	v_mfma_f32_16x16x32_bf16 v[28:31], v[156:159], v[172:175], v[28:31]
	v_mfma_f32_16x16x32_bf16 v[16:19], v[148:151], v[180:183], v[16:19]
	v_mfma_f32_16x16x32_bf16 v[12:15], v[156:159], v[180:183], v[12:15]
	v_mfma_f32_16x16x32_bf16 v[4:7], v[148:151], v[188:191], v[4:7]
	v_mfma_f32_16x16x32_bf16 v[0:3], v[156:159], v[188:191], v[0:3]
	s_setprio 0
	s_barrier
	s_add_i32 s79, s79, 2
	s_add_u32 s34, s34, 0x100
	s_addc_u32 s35, s35, 0
	s_mov_b64 s[24:25], s[10:11]

.LBB0_97:
	s_add_u32 s10, s70, 0x12140000
	v_lshrrev_b32_e32 v16, 1, v14
	s_addc_u32 s11, s71, 0
	v_and_b32_e32 v16, 24, v16
	s_lshl_b32 s0, s0, 5
	s_sext_i32_i16 s23, s6
	v_and_b32_e32 v15, 15, v14
	v_lshlrev_b32_e32 v17, 1, v16
	v_lshlrev_b32_e32 v14, 2, v14
	s_and_b32 s6, s0, 0x60
	s_add_i32 m0, s40, 0x18000
	v_lshl_add_u64 v[6:7], v[6:7], 0, s[54:55]
	v_lshl_or_b32 v146, s1, 6, v15
	v_lshl_or_b32 v15, v15, 6, v17
	s_lshl_b32 s1, s1, 13
	v_and_b32_e32 v14, 32, v14
	s_lshl_b32 s0, s6, 7
	s_waitcnt vmcnt(2)
	s_barrier
	global_load_lds_dwordx4 v[6:7], off
	v_lshl_add_u64 v[4:5], v[4:5], 0, s[54:55]
	s_add_i32 m0, s40, 0x1a000
	s_add_i32 s47, s40, 0x8000
	s_add_i32 s48, s40, 0xa000
	v_bitop3_b32 v147, s0, v15, v14 bitop3:0xf6
	global_load_lds_dwordx4 v[4:5], off
	v_lshl_add_u64 v[0:1], v[0:1], 0, s[54:55]
	s_mov_b32 m0, s47
	s_add_u32 s0, s28, 0x80080
	v_bitop3_b32 v17, v15, s1, v14 bitop3:0xde
	global_load_lds_dwordx4 v[0:1], off
	v_lshl_add_u64 v[0:1], v[2:3], 0, s[54:55]
	s_mov_b32 m0, s48
	s_addc_u32 s1, s29, 0
	global_load_lds_dwordx4 v[0:1], off
	s_add_i32 m0, s40, 0x1c000
	v_lshl_add_u64 v[0:1], s[0:1], 0, v[198:199]
	global_load_lds_dwordx4 v[0:1], off
	v_lshl_add_u64 v[0:1], s[0:1], 0, v[128:129]
	s_add_i32 m0, s40, 0x1e000
	s_waitcnt lgkmcnt(0)
	s_ashr_i32 s49, s46, 31
	global_load_lds_dwordx4 v[0:1], off
	v_lshlrev_b32_e32 v0, 15, v12
	v_and_b32_e32 v0, 0xffff0000, v0
	v_lshl_add_u32 v0, v11, 12, v0
	v_and_b32_e32 v1, 1, v12
	v_lshl_or_b32 v0, v1, 6, v0
	v_lshl_add_u32 v134, v13, 1, v0
	v_lshlrev_b32_e32 v0, 15, v8
	v_and_b32_e32 v0, 0xffff0000, v0
	s_waitcnt vmcnt(0)
	v_lshl_add_u32 v0, v9, 12, v0
	v_and_b32_e32 v1, 1, v8
	s_cmpk_lt_u32 s7, 0x100
	v_lshl_or_b32 v0, v1, 6, v0
	s_cselect_b64 s[12:13], -1, 0
	v_or_b32_e32 v148, s6, v16
	v_mov_b32_e32 v135, v199
	v_lshl_add_u32 v136, v10, 1, v0
	v_mov_b32_e32 v137, v199
	s_mov_b32 s50, 0
	v_add_u32_e32 v149, 0, v17
	s_barrier
	s_branch .LBB0_100

.LBB0_102:
	s_ashr_i32 s17, s16, 31
	s_lshl_b64 s[0:1], s[16:17], 20
	s_add_u32 s18, s26, s0
	s_addc_u32 s19, s27, s1
	s_and_b64 s[0:1], s[6:7], exec
	s_cselect_b32 s17, s19, s25
	s_cselect_b32 s51, s18, s24
	s_ashr_i32 s15, s14, 31
	s_lshl_b64 s[0:1], s[14:15], 20
	s_add_u32 s20, s36, s0
	s_addc_u32 s21, s37, s1
	s_and_b64 s[0:1], s[6:7], exec
	s_cselect_b32 s15, s21, s29
	s_cselect_b32 s34, s20, s28
	s_add_u32 s24, s24, 0x80080
	s_addc_u32 s25, s25, 0
	s_add_u32 s35, s28, 0x100
	s_addc_u32 s52, s29, 0
	s_mov_b32 s61, -2
	s_add_u32 s0, s24, 0xfff80080
	s_addc_u32 s1, s25, -1
	s_add_i32 s59, 0, 0x10000
	s_cmp_eq_u32 s61, 28
	s_cselect_b32 s31, s17, s1
	s_cselect_b32 s30, s51, s0
	s_cselect_b32 s29, s15, s52
	s_cselect_b32 s28, s34, s35
	s_add_i32 s63, 0, 0x14000
	v_add_u32_e32 v154, s59, v147
	v_add_u32_e32 v170, s63, v147
	ds_read_b128 v[138:141], v154
	ds_read_b128 v[142:145], v154 offset:1024
	ds_read_b128 v[150:153], v154 offset:2048
	ds_read_b128 v[154:157], v154 offset:3072
	ds_read_b128 v[158:161], v170
	ds_read_b128 v[162:165], v170 offset:1024
	ds_read_b128 v[166:169], v170 offset:2048
	ds_read_b128 v[170:173], v170 offset:3072
	v_lshl_add_u64 v[220:221], s[24:25], 0, v[134:135]
	s_add_i32 m0, s40, 0xc000
	ds_read_b128 v[174:177], v149
	ds_read_b128 v[178:181], v149 offset:1024
	ds_read_b128 v[182:185], v149 offset:2048
	ds_read_b128 v[186:189], v149 offset:3072
	ds_read_b128 v[190:193], v149 offset:4096
	ds_read_b128 v[194:197], v149 offset:5120
	ds_read_b128 v[212:215], v149 offset:6144
	ds_read_b128 v[216:219], v149 offset:7168
	global_load_lds_dwordx4 v[220:221], off
	v_lshl_add_u64 v[220:221], s[24:25], 0, v[136:137]
	s_add_i32 m0, s40, 0xe000
	s_nop 0
	global_load_lds_dwordx4 v[220:221], off
	s_waitcnt vmcnt(63)
	s_waitcnt lgkmcnt(0)
	s_barrier
	s_setprio 1
	s_waitcnt lgkmcnt(0)
	v_mfma_f32_16x16x32_bf16 v[124:127], v[138:141], v[174:177], 0
	v_mfma_f32_16x16x32_bf16 v[116:119], v[150:153], v[174:177], 0
	v_mfma_f32_16x16x32_bf16 v[108:111], v[138:141], v[182:185], 0
	v_mfma_f32_16x16x32_bf16 v[96:99], v[150:153], v[182:185], 0
	v_mfma_f32_16x16x32_bf16 v[88:91], v[138:141], v[190:193], 0
	v_mfma_f32_16x16x32_bf16 v[80:83], v[150:153], v[190:193], 0
	v_mfma_f32_16x16x32_bf16 v[72:75], v[138:141], v[212:215], 0
	v_mfma_f32_16x16x32_bf16 v[64:67], v[150:153], v[212:215], 0
	v_mfma_f32_16x16x32_bf16 v[124:127], v[142:145], v[178:181], v[124:127]
	v_mfma_f32_16x16x32_bf16 v[116:119], v[154:157], v[178:181], v[116:119]
	v_mfma_f32_16x16x32_bf16 v[108:111], v[142:145], v[186:189], v[108:111]
	v_mfma_f32_16x16x32_bf16 v[96:99], v[154:157], v[186:189], v[96:99]
	v_mfma_f32_16x16x32_bf16 v[88:91], v[142:145], v[194:197], v[88:91]
	v_mfma_f32_16x16x32_bf16 v[80:83], v[154:157], v[194:197], v[80:83]
	v_mfma_f32_16x16x32_bf16 v[72:75], v[142:145], v[216:219], v[72:75]
	v_mfma_f32_16x16x32_bf16 v[64:67], v[154:157], v[216:219], v[64:67]
	s_setprio 0
	s_setprio 1
	v_mfma_f32_16x16x32_bf16 v[120:123], v[158:161], v[174:177], 0
	v_mfma_f32_16x16x32_bf16 v[112:115], v[166:169], v[174:177], 0
	v_mfma_f32_16x16x32_bf16 v[104:107], v[158:161], v[182:185], 0
	v_mfma_f32_16x16x32_bf16 v[100:103], v[166:169], v[182:185], 0
	v_mfma_f32_16x16x32_bf16 v[92:95], v[158:161], v[190:193], 0
	v_mfma_f32_16x16x32_bf16 v[84:87], v[166:169], v[190:193], 0
	v_mfma_f32_16x16x32_bf16 v[76:79], v[158:161], v[212:215], 0
	v_mfma_f32_16x16x32_bf16 v[68:71], v[166:169], v[212:215], 0
	v_mfma_f32_16x16x32_bf16 v[120:123], v[162:165], v[178:181], v[120:123]
	v_mfma_f32_16x16x32_bf16 v[112:115], v[170:173], v[178:181], v[112:115]
	v_mfma_f32_16x16x32_bf16 v[104:107], v[162:165], v[186:189], v[104:107]
	v_mfma_f32_16x16x32_bf16 v[100:103], v[170:173], v[186:189], v[100:103]
	v_mfma_f32_16x16x32_bf16 v[92:95], v[162:165], v[194:197], v[92:95]
	v_mfma_f32_16x16x32_bf16 v[84:87], v[170:173], v[194:197], v[84:87]
	v_mfma_f32_16x16x32_bf16 v[76:79], v[162:165], v[216:219], v[76:79]
	v_mfma_f32_16x16x32_bf16 v[68:71], v[170:173], v[216:219], v[68:71]
	s_setprio 0
	s_barrier
	s_add_i32 s0, s59, s38
	v_lshl_add_u64 v[220:221], s[28:29], 0, v[198:199]
	s_mov_b32 m0, s0
	ds_read_b128 v[174:177], v149 offset:16384
	ds_read_b128 v[178:181], v149 offset:17408
	ds_read_b128 v[182:185], v149 offset:18432
	ds_read_b128 v[186:189], v149 offset:19456
	ds_read_b128 v[190:193], v149 offset:20480
	ds_read_b128 v[194:197], v149 offset:21504
	ds_read_b128 v[212:215], v149 offset:22528
	ds_read_b128 v[216:219], v149 offset:23552
	global_load_lds_dwordx4 v[220:221], off
	s_add_i32 m0, s0, 0x2000
	s_add_u32 s0, s28, 0x80000
	v_lshl_add_u64 v[222:223], s[28:29], 0, v[128:129]
	s_addc_u32 s1, s29, 0
	s_add_i32 s59, s63, s38
	global_load_lds_dwordx4 v[222:223], off
	v_lshl_add_u64 v[224:225], s[0:1], 0, v[198:199]
	s_mov_b32 m0, s59
	v_lshl_add_u64 v[226:227], s[30:31], 0, v[130:131]
	global_load_lds_dwordx4 v[224:225], off
	v_lshl_add_u64 v[224:225], s[0:1], 0, v[128:129]
	s_add_i32 m0, s59, 0x2000
	s_nop 0
	global_load_lds_dwordx4 v[224:225], off
	v_lshl_add_u64 v[224:225], s[30:31], 0, v[132:133]
	s_mov_b32 m0, s40
	s_nop 0
	global_load_lds_dwordx4 v[224:225], off
	s_mov_b32 m0, s41
	s_nop 0
	global_load_lds_dwordx4 v[226:227], off
	s_waitcnt vmcnt(63)
	s_waitcnt lgkmcnt(0)
	s_barrier
	s_setprio 1
	s_waitcnt lgkmcnt(0)
	v_mfma_f32_16x16x32_bf16 v[56:59], v[138:141], v[174:177], 0
	v_mfma_f32_16x16x32_bf16 v[48:51], v[150:153], v[174:177], 0
	v_mfma_f32_16x16x32_bf16 v[40:43], v[138:141], v[182:185], 0
	v_mfma_f32_16x16x32_bf16 v[32:35], v[150:153], v[182:185], 0
	v_mfma_f32_16x16x32_bf16 v[24:27], v[138:141], v[190:193], 0
	v_mfma_f32_16x16x32_bf16 v[16:19], v[150:153], v[190:193], 0
	v_mfma_f32_16x16x32_bf16 v[8:11], v[138:141], v[212:215], 0
	v_mfma_f32_16x16x32_bf16 v[0:3], v[150:153], v[212:215], 0
	v_mfma_f32_16x16x32_bf16 v[56:59], v[142:145], v[178:181], v[56:59]
	v_mfma_f32_16x16x32_bf16 v[48:51], v[154:157], v[178:181], v[48:51]
	v_mfma_f32_16x16x32_bf16 v[40:43], v[142:145], v[186:189], v[40:43]
	v_mfma_f32_16x16x32_bf16 v[32:35], v[154:157], v[186:189], v[32:35]
	v_mfma_f32_16x16x32_bf16 v[24:27], v[142:145], v[194:197], v[24:27]
	v_mfma_f32_16x16x32_bf16 v[16:19], v[154:157], v[194:197], v[16:19]
	v_mfma_f32_16x16x32_bf16 v[8:11], v[142:145], v[216:219], v[8:11]
	v_mfma_f32_16x16x32_bf16 v[0:3], v[154:157], v[216:219], v[0:3]
	s_setprio 0
	s_setprio 1
	v_mfma_f32_16x16x32_bf16 v[60:63], v[158:161], v[174:177], 0
	v_mfma_f32_16x16x32_bf16 v[52:55], v[166:169], v[174:177], 0
	v_mfma_f32_16x16x32_bf16 v[44:47], v[158:161], v[182:185], 0
	v_mfma_f32_16x16x32_bf16 v[36:39], v[166:169], v[182:185], 0
	v_mfma_f32_16x16x32_bf16 v[28:31], v[158:161], v[190:193], 0
	v_mfma_f32_16x16x32_bf16 v[20:23], v[166:169], v[190:193], 0
	v_mfma_f32_16x16x32_bf16 v[12:15], v[158:161], v[212:215], 0
	v_mfma_f32_16x16x32_bf16 v[4:7], v[166:169], v[212:215], 0
	v_mfma_f32_16x16x32_bf16 v[60:63], v[162:165], v[178:181], v[60:63]
	v_mfma_f32_16x16x32_bf16 v[52:55], v[170:173], v[178:181], v[52:55]
	v_mfma_f32_16x16x32_bf16 v[44:47], v[162:165], v[186:189], v[44:47]
	v_mfma_f32_16x16x32_bf16 v[36:39], v[170:173], v[186:189], v[36:39]
	v_mfma_f32_16x16x32_bf16 v[28:31], v[162:165], v[194:197], v[28:31]
	v_mfma_f32_16x16x32_bf16 v[20:23], v[170:173], v[194:197], v[20:23]
	v_mfma_f32_16x16x32_bf16 v[12:15], v[162:165], v[216:219], v[12:15]
	v_mfma_f32_16x16x32_bf16 v[4:7], v[170:173], v[216:219], v[4:7]
	s_setprio 0
	s_barrier
	s_add_i32 s59, 0, 0x18000
	s_add_i32 s63, 0, 0x1c000
	v_add_u32_e32 v154, s59, v147
	v_add_u32_e32 v170, s63, v147
	ds_read_b128 v[138:141], v154
	ds_read_b128 v[142:145], v154 offset:1024
	ds_read_b128 v[150:153], v154 offset:2048
	ds_read_b128 v[154:157], v154 offset:3072
	ds_read_b128 v[158:161], v170
	ds_read_b128 v[162:165], v170 offset:1024
	ds_read_b128 v[166:169], v170 offset:2048
	ds_read_b128 v[170:173], v170 offset:3072
	s_add_u32 s0, s30, 0x80000
	s_addc_u32 s1, s31, 0
	s_mov_b32 m0, s42
	v_lshl_add_u64 v[228:229], s[0:1], 0, v[132:133]
	ds_read_b128 v[174:177], v149 offset:32768
	ds_read_b128 v[178:181], v149 offset:33792
	ds_read_b128 v[182:185], v149 offset:34816
	ds_read_b128 v[186:189], v149 offset:35840
	ds_read_b128 v[190:193], v149 offset:36864
	ds_read_b128 v[194:197], v149 offset:37888
	ds_read_b128 v[212:215], v149 offset:38912
	ds_read_b128 v[216:219], v149 offset:39936
	global_load_lds_dwordx4 v[228:229], off
	v_lshl_add_u64 v[228:229], s[0:1], 0, v[130:131]
	s_mov_b32 m0, s43
	s_nop 0
	global_load_lds_dwordx4 v[228:229], off
	s_waitcnt vmcnt(8)
	s_waitcnt lgkmcnt(0)
	s_barrier
	s_setprio 1
	s_waitcnt lgkmcnt(0)
	v_mfma_f32_16x16x32_bf16 v[124:127], v[138:141], v[174:177], v[124:127]
	v_mfma_f32_16x16x32_bf16 v[116:119], v[150:153], v[174:177], v[116:119]
	v_mfma_f32_16x16x32_bf16 v[108:111], v[138:141], v[182:185], v[108:111]
	v_mfma_f32_16x16x32_bf16 v[96:99], v[150:153], v[182:185], v[96:99]
	v_mfma_f32_16x16x32_bf16 v[88:91], v[138:141], v[190:193], v[88:91]
	v_mfma_f32_16x16x32_bf16 v[80:83], v[150:153], v[190:193], v[80:83]
	v_mfma_f32_16x16x32_bf16 v[72:75], v[138:141], v[212:215], v[72:75]
	v_mfma_f32_16x16x32_bf16 v[64:67], v[150:153], v[212:215], v[64:67]
	v_mfma_f32_16x16x32_bf16 v[124:127], v[142:145], v[178:181], v[124:127]
	v_mfma_f32_16x16x32_bf16 v[116:119], v[154:157], v[178:181], v[116:119]
	v_mfma_f32_16x16x32_bf16 v[108:111], v[142:145], v[186:189], v[108:111]
	v_mfma_f32_16x16x32_bf16 v[96:99], v[154:157], v[186:189], v[96:99]
	v_mfma_f32_16x16x32_bf16 v[88:91], v[142:145], v[194:197], v[88:91]
	v_mfma_f32_16x16x32_bf16 v[80:83], v[154:157], v[194:197], v[80:83]
	v_mfma_f32_16x16x32_bf16 v[72:75], v[142:145], v[216:219], v[72:75]
	v_mfma_f32_16x16x32_bf16 v[64:67], v[154:157], v[216:219], v[64:67]
	s_setprio 0
	s_setprio 1
	v_mfma_f32_16x16x32_bf16 v[120:123], v[158:161], v[174:177], v[120:123]
	v_mfma_f32_16x16x32_bf16 v[112:115], v[166:169], v[174:177], v[112:115]
	v_mfma_f32_16x16x32_bf16 v[104:107], v[158:161], v[182:185], v[104:107]
	v_mfma_f32_16x16x32_bf16 v[100:103], v[166:169], v[182:185], v[100:103]
	v_mfma_f32_16x16x32_bf16 v[92:95], v[158:161], v[190:193], v[92:95]
	v_mfma_f32_16x16x32_bf16 v[84:87], v[166:169], v[190:193], v[84:87]
	v_mfma_f32_16x16x32_bf16 v[76:79], v[158:161], v[212:215], v[76:79]
	v_mfma_f32_16x16x32_bf16 v[68:71], v[166:169], v[212:215], v[68:71]
	v_mfma_f32_16x16x32_bf16 v[120:123], v[162:165], v[178:181], v[120:123]
	v_mfma_f32_16x16x32_bf16 v[112:115], v[170:173], v[178:181], v[112:115]
	v_mfma_f32_16x16x32_bf16 v[104:107], v[162:165], v[186:189], v[104:107]
	v_mfma_f32_16x16x32_bf16 v[100:103], v[170:173], v[186:189], v[100:103]
	v_mfma_f32_16x16x32_bf16 v[92:95], v[162:165], v[194:197], v[92:95]
	v_mfma_f32_16x16x32_bf16 v[84:87], v[170:173], v[194:197], v[84:87]
	v_mfma_f32_16x16x32_bf16 v[76:79], v[162:165], v[216:219], v[76:79]
	v_mfma_f32_16x16x32_bf16 v[68:71], v[170:173], v[216:219], v[68:71]
	s_setprio 0
	s_barrier
	s_add_i32 s0, s59, s38
	v_lshl_add_u64 v[220:221], v[220:221], 0, s[54:55]
	s_mov_b32 m0, s0
	ds_read_b128 v[174:177], v149 offset:49152
	ds_read_b128 v[178:181], v149 offset:50176
	ds_read_b128 v[182:185], v149 offset:51200
	ds_read_b128 v[186:189], v149 offset:52224
	ds_read_b128 v[190:193], v149 offset:53248
	ds_read_b128 v[194:197], v149 offset:54272
	ds_read_b128 v[212:215], v149 offset:55296
	ds_read_b128 v[216:219], v149 offset:56320
	global_load_lds_dwordx4 v[220:221], off
	s_add_i32 m0, s0, 0x2000
	s_add_u32 s0, s28, 0x80080
	v_lshl_add_u64 v[220:221], v[222:223], 0, s[54:55]
	s_addc_u32 s1, s29, 0
	s_add_i32 s28, s63, s38
	global_load_lds_dwordx4 v[220:221], off
	v_lshl_add_u64 v[220:221], s[0:1], 0, v[198:199]
	s_mov_b32 m0, s28
	s_nop 0
	global_load_lds_dwordx4 v[220:221], off
	v_lshl_add_u64 v[220:221], s[0:1], 0, v[128:129]
	s_add_i32 m0, s28, 0x2000
	s_nop 0
	global_load_lds_dwordx4 v[220:221], off
	v_lshl_add_u64 v[220:221], v[224:225], 0, s[54:55]
	s_mov_b32 m0, s47
	s_nop 0
	global_load_lds_dwordx4 v[220:221], off
	v_lshl_add_u64 v[220:221], v[226:227], 0, s[54:55]
	s_mov_b32 m0, s48
	s_nop 0
	global_load_lds_dwordx4 v[220:221], off
	s_waitcnt vmcnt(8)
	s_waitcnt lgkmcnt(0)
	s_barrier
	s_setprio 1
	s_waitcnt lgkmcnt(0)
	v_mfma_f32_16x16x32_bf16 v[56:59], v[138:141], v[174:177], v[56:59]
	v_mfma_f32_16x16x32_bf16 v[48:51], v[150:153], v[174:177], v[48:51]
	v_mfma_f32_16x16x32_bf16 v[40:43], v[138:141], v[182:185], v[40:43]
	v_mfma_f32_16x16x32_bf16 v[32:35], v[150:153], v[182:185], v[32:35]
	v_mfma_f32_16x16x32_bf16 v[24:27], v[138:141], v[190:193], v[24:27]
	v_mfma_f32_16x16x32_bf16 v[16:19], v[150:153], v[190:193], v[16:19]
	v_mfma_f32_16x16x32_bf16 v[8:11], v[138:141], v[212:215], v[8:11]
	v_mfma_f32_16x16x32_bf16 v[0:3], v[150:153], v[212:215], v[0:3]
	v_mfma_f32_16x16x32_bf16 v[56:59], v[142:145], v[178:181], v[56:59]
	v_mfma_f32_16x16x32_bf16 v[48:51], v[154:157], v[178:181], v[48:51]
	v_mfma_f32_16x16x32_bf16 v[40:43], v[142:145], v[186:189], v[40:43]
	v_mfma_f32_16x16x32_bf16 v[32:35], v[154:157], v[186:189], v[32:35]
	v_mfma_f32_16x16x32_bf16 v[24:27], v[142:145], v[194:197], v[24:27]
	v_mfma_f32_16x16x32_bf16 v[16:19], v[154:157], v[194:197], v[16:19]
	v_mfma_f32_16x16x32_bf16 v[8:11], v[142:145], v[216:219], v[8:11]
	v_mfma_f32_16x16x32_bf16 v[0:3], v[154:157], v[216:219], v[0:3]
	s_setprio 0
	s_setprio 1
	v_mfma_f32_16x16x32_bf16 v[60:63], v[158:161], v[174:177], v[60:63]
	v_mfma_f32_16x16x32_bf16 v[52:55], v[166:169], v[174:177], v[52:55]
	v_mfma_f32_16x16x32_bf16 v[44:47], v[158:161], v[182:185], v[44:47]
	v_mfma_f32_16x16x32_bf16 v[36:39], v[166:169], v[182:185], v[36:39]
	v_mfma_f32_16x16x32_bf16 v[28:31], v[158:161], v[190:193], v[28:31]
	v_mfma_f32_16x16x32_bf16 v[20:23], v[166:169], v[190:193], v[20:23]
	v_mfma_f32_16x16x32_bf16 v[12:15], v[158:161], v[212:215], v[12:15]
	v_mfma_f32_16x16x32_bf16 v[4:7], v[166:169], v[212:215], v[4:7]
	v_mfma_f32_16x16x32_bf16 v[60:63], v[162:165], v[178:181], v[60:63]
	v_mfma_f32_16x16x32_bf16 v[52:55], v[170:173], v[178:181], v[52:55]
	v_mfma_f32_16x16x32_bf16 v[44:47], v[162:165], v[186:189], v[44:47]
	v_mfma_f32_16x16x32_bf16 v[36:39], v[170:173], v[186:189], v[36:39]
	v_mfma_f32_16x16x32_bf16 v[28:31], v[162:165], v[194:197], v[28:31]
	v_mfma_f32_16x16x32_bf16 v[20:23], v[170:173], v[194:197], v[20:23]
	v_mfma_f32_16x16x32_bf16 v[12:15], v[162:165], v[216:219], v[12:15]
	v_mfma_f32_16x16x32_bf16 v[4:7], v[170:173], v[216:219], v[4:7]
	s_setprio 0
	s_barrier
	s_add_i32 s61, s61, 2
	s_add_u32 s24, s24, 0x100
	s_addc_u32 s25, s25, 0
	s_add_u32 s35, s35, 0x100
	s_addc_u32 s52, s52, 0

.LBB0_455:
	s_add_u32 s10, s70, 0x12140000
	v_lshrrev_b32_e32 v16, 1, v14
	s_addc_u32 s11, s71, 0
	v_and_b32_e32 v16, 24, v16
	s_lshl_b32 s0, s0, 5
	s_sext_i32_i8 s29, s6
	v_and_b32_e32 v15, 15, v14
	v_lshlrev_b32_e32 v17, 1, v16
	v_lshlrev_b32_e32 v14, 2, v14
	s_and_b32 s6, s0, 0x60
	s_add_i32 m0, s44, 0x18000
	v_lshl_add_u64 v[6:7], v[6:7], 0, s[54:55]
	v_lshl_or_b32 v146, s1, 6, v15
	v_lshl_or_b32 v15, v15, 6, v17
	s_lshl_b32 s1, s1, 13
	v_and_b32_e32 v14, 32, v14
	s_lshl_b32 s0, s6, 7
	s_waitcnt vmcnt(2)
	s_barrier
	global_load_lds_dwordx4 v[6:7], off
	v_lshl_add_u64 v[4:5], v[4:5], 0, s[54:55]
	s_add_i32 m0, s44, 0x1a000
	s_add_i32 s49, s44, 0x8000
	s_add_i32 s50, s44, 0xa000
	v_bitop3_b32 v147, s0, v15, v14 bitop3:0xf6
	global_load_lds_dwordx4 v[4:5], off
	v_lshl_add_u64 v[0:1], v[0:1], 0, s[54:55]
	s_mov_b32 m0, s49
	s_add_u32 s0, s36, 0x80080
	v_bitop3_b32 v17, v15, s1, v14 bitop3:0xde
	global_load_lds_dwordx4 v[0:1], off
	v_lshl_add_u64 v[0:1], v[2:3], 0, s[54:55]
	s_mov_b32 m0, s50
	s_addc_u32 s1, s37, 0
	global_load_lds_dwordx4 v[0:1], off
	s_add_i32 m0, s44, 0x1c000
	v_lshl_add_u64 v[0:1], s[0:1], 0, v[198:199]
	global_load_lds_dwordx4 v[0:1], off
	v_lshl_add_u64 v[0:1], s[0:1], 0, v[128:129]
	s_add_i32 m0, s44, 0x1e000
	s_waitcnt lgkmcnt(0)
	s_ashr_i32 s51, s48, 31
	global_load_lds_dwordx4 v[0:1], off
	v_lshlrev_b32_e32 v0, 15, v12
	v_and_b32_e32 v0, 0xffff0000, v0
	v_lshl_add_u32 v0, v11, 12, v0
	v_and_b32_e32 v1, 1, v12
	v_lshl_or_b32 v0, v1, 6, v0
	v_lshl_add_u32 v134, v13, 1, v0
	v_lshlrev_b32_e32 v0, 15, v8
	v_and_b32_e32 v0, 0xffff0000, v0
	s_waitcnt vmcnt(0)
	v_lshl_add_u32 v0, v9, 12, v0
	v_and_b32_e32 v1, 1, v8
	s_cmpk_lt_u32 s7, 0x100
	v_lshl_or_b32 v0, v1, 6, v0
	s_cselect_b64 s[12:13], -1, 0
	v_or_b32_e32 v148, s6, v16
	v_mov_b32_e32 v135, v199
	v_lshl_add_u32 v136, v10, 1, v0
	v_mov_b32_e32 v137, v199
	s_mov_b32 s52, 0
	v_add_u32_e32 v149, 0, v17
	s_barrier
	s_branch .LBB0_458

.LBB0_460:
	s_ashr_i32 s17, s16, 31
	s_lshl_b64 s[0:1], s[16:17], 20
	s_add_u32 s18, s26, s0
	s_addc_u32 s19, s27, s1
	s_and_b64 s[0:1], s[6:7], exec
	s_cselect_b32 s17, s19, s31
	s_cselect_b32 s61, s18, s30
	s_ashr_i32 s15, s14, 31
	s_lshl_b64 s[0:1], s[14:15], 20
	s_add_u32 s20, s40, s0
	s_addc_u32 s21, s41, s1
	s_and_b64 s[0:1], s[6:7], exec
	s_cselect_b32 s15, s21, s37
	s_cselect_b32 s34, s20, s36
	s_add_u32 s30, s30, 0x80080
	s_addc_u32 s31, s31, 0
	s_add_u32 s35, s36, 0x100
	s_addc_u32 s69, s37, 0
	s_mov_b32 s79, -2
	s_add_u32 s0, s30, 0xfff80080
	s_addc_u32 s1, s31, -1
	s_add_i32 s59, 0, 0x10000
	s_cmp_eq_u32 s79, 28
	s_cselect_b32 s39, s17, s1
	s_cselect_b32 s38, s61, s0
	s_cselect_b32 s37, s15, s69
	s_cselect_b32 s36, s34, s35
	s_add_i32 s63, 0, 0x14000
	v_add_u32_e32 v154, s59, v147
	v_add_u32_e32 v170, s63, v147
	ds_read_b128 v[138:141], v154
	ds_read_b128 v[142:145], v154 offset:1024
	ds_read_b128 v[150:153], v154 offset:2048
	ds_read_b128 v[154:157], v154 offset:3072
	ds_read_b128 v[158:161], v170
	ds_read_b128 v[162:165], v170 offset:1024
	ds_read_b128 v[166:169], v170 offset:2048
	ds_read_b128 v[170:173], v170 offset:3072
	v_lshl_add_u64 v[220:221], s[30:31], 0, v[134:135]
	s_add_i32 m0, s44, 0xc000
	ds_read_b128 v[174:177], v149
	ds_read_b128 v[178:181], v149 offset:1024
	ds_read_b128 v[182:185], v149 offset:2048
	ds_read_b128 v[186:189], v149 offset:3072
	ds_read_b128 v[190:193], v149 offset:4096
	ds_read_b128 v[194:197], v149 offset:5120
	ds_read_b128 v[212:215], v149 offset:6144
	ds_read_b128 v[216:219], v149 offset:7168
	global_load_lds_dwordx4 v[220:221], off
	v_lshl_add_u64 v[220:221], s[30:31], 0, v[136:137]
	s_add_i32 m0, s44, 0xe000
	s_nop 0
	global_load_lds_dwordx4 v[220:221], off
	s_waitcnt vmcnt(63)
	s_waitcnt lgkmcnt(0)
	s_barrier
	s_setprio 1
	s_waitcnt lgkmcnt(0)
	v_mfma_f32_16x16x32_bf16 v[124:127], v[138:141], v[174:177], 0
	v_mfma_f32_16x16x32_bf16 v[120:123], v[150:153], v[174:177], 0
	v_mfma_f32_16x16x32_bf16 v[108:111], v[138:141], v[182:185], 0
	v_mfma_f32_16x16x32_bf16 v[104:107], v[150:153], v[182:185], 0
	v_mfma_f32_16x16x32_bf16 v[92:95], v[138:141], v[190:193], 0
	v_mfma_f32_16x16x32_bf16 v[88:91], v[150:153], v[190:193], 0
	v_mfma_f32_16x16x32_bf16 v[76:79], v[138:141], v[212:215], 0
	v_mfma_f32_16x16x32_bf16 v[72:75], v[150:153], v[212:215], 0
	v_mfma_f32_16x16x32_bf16 v[124:127], v[142:145], v[178:181], v[124:127]
	v_mfma_f32_16x16x32_bf16 v[120:123], v[154:157], v[178:181], v[120:123]
	v_mfma_f32_16x16x32_bf16 v[108:111], v[142:145], v[186:189], v[108:111]
	v_mfma_f32_16x16x32_bf16 v[104:107], v[154:157], v[186:189], v[104:107]
	v_mfma_f32_16x16x32_bf16 v[92:95], v[142:145], v[194:197], v[92:95]
	v_mfma_f32_16x16x32_bf16 v[88:91], v[154:157], v[194:197], v[88:91]
	v_mfma_f32_16x16x32_bf16 v[76:79], v[142:145], v[216:219], v[76:79]
	v_mfma_f32_16x16x32_bf16 v[72:75], v[154:157], v[216:219], v[72:75]
	s_setprio 0
	s_setprio 1
	v_mfma_f32_16x16x32_bf16 v[116:119], v[158:161], v[174:177], 0
	v_mfma_f32_16x16x32_bf16 v[112:115], v[166:169], v[174:177], 0
	v_mfma_f32_16x16x32_bf16 v[100:103], v[158:161], v[182:185], 0
	v_mfma_f32_16x16x32_bf16 v[96:99], v[166:169], v[182:185], 0
	v_mfma_f32_16x16x32_bf16 v[84:87], v[158:161], v[190:193], 0
	v_mfma_f32_16x16x32_bf16 v[80:83], v[166:169], v[190:193], 0
	v_mfma_f32_16x16x32_bf16 v[68:71], v[158:161], v[212:215], 0
	v_mfma_f32_16x16x32_bf16 v[64:67], v[166:169], v[212:215], 0
	v_mfma_f32_16x16x32_bf16 v[116:119], v[162:165], v[178:181], v[116:119]
	v_mfma_f32_16x16x32_bf16 v[112:115], v[170:173], v[178:181], v[112:115]
	v_mfma_f32_16x16x32_bf16 v[100:103], v[162:165], v[186:189], v[100:103]
	v_mfma_f32_16x16x32_bf16 v[96:99], v[170:173], v[186:189], v[96:99]
	v_mfma_f32_16x16x32_bf16 v[84:87], v[162:165], v[194:197], v[84:87]
	v_mfma_f32_16x16x32_bf16 v[80:83], v[170:173], v[194:197], v[80:83]
	v_mfma_f32_16x16x32_bf16 v[68:71], v[162:165], v[216:219], v[68:71]
	v_mfma_f32_16x16x32_bf16 v[64:67], v[170:173], v[216:219], v[64:67]
	s_setprio 0
	s_barrier
	s_add_i32 s0, s59, s42
	v_lshl_add_u64 v[220:221], s[36:37], 0, v[198:199]
	s_mov_b32 m0, s0
	ds_read_b128 v[174:177], v149 offset:16384
	ds_read_b128 v[178:181], v149 offset:17408
	ds_read_b128 v[182:185], v149 offset:18432
	ds_read_b128 v[186:189], v149 offset:19456
	ds_read_b128 v[190:193], v149 offset:20480
	ds_read_b128 v[194:197], v149 offset:21504
	ds_read_b128 v[212:215], v149 offset:22528
	ds_read_b128 v[216:219], v149 offset:23552
	global_load_lds_dwordx4 v[220:221], off
	s_add_i32 m0, s0, 0x2000
	s_add_u32 s0, s36, 0x80000
	v_lshl_add_u64 v[222:223], s[36:37], 0, v[128:129]
	s_addc_u32 s1, s37, 0
	s_add_i32 s59, s63, s42
	global_load_lds_dwordx4 v[222:223], off
	v_lshl_add_u64 v[224:225], s[0:1], 0, v[198:199]
	s_mov_b32 m0, s59
	v_lshl_add_u64 v[226:227], s[38:39], 0, v[130:131]
	global_load_lds_dwordx4 v[224:225], off
	v_lshl_add_u64 v[224:225], s[0:1], 0, v[128:129]
	s_add_i32 m0, s59, 0x2000
	s_nop 0
	global_load_lds_dwordx4 v[224:225], off
	v_lshl_add_u64 v[224:225], s[38:39], 0, v[132:133]
	s_mov_b32 m0, s44
	s_nop 0
	global_load_lds_dwordx4 v[224:225], off
	s_mov_b32 m0, s45
	s_nop 0
	global_load_lds_dwordx4 v[226:227], off
	s_waitcnt vmcnt(63)
	s_waitcnt lgkmcnt(0)
	s_barrier
	s_setprio 1
	s_waitcnt lgkmcnt(0)
	v_mfma_f32_16x16x32_bf16 v[60:63], v[138:141], v[174:177], 0
	v_mfma_f32_16x16x32_bf16 v[56:59], v[150:153], v[174:177], 0
	v_mfma_f32_16x16x32_bf16 v[44:47], v[138:141], v[182:185], 0
	v_mfma_f32_16x16x32_bf16 v[40:43], v[150:153], v[182:185], 0
	v_mfma_f32_16x16x32_bf16 v[28:31], v[138:141], v[190:193], 0
	v_mfma_f32_16x16x32_bf16 v[24:27], v[150:153], v[190:193], 0
	v_mfma_f32_16x16x32_bf16 v[12:15], v[138:141], v[212:215], 0
	v_mfma_f32_16x16x32_bf16 v[8:11], v[150:153], v[212:215], 0
	v_mfma_f32_16x16x32_bf16 v[60:63], v[142:145], v[178:181], v[60:63]
	v_mfma_f32_16x16x32_bf16 v[56:59], v[154:157], v[178:181], v[56:59]
	v_mfma_f32_16x16x32_bf16 v[44:47], v[142:145], v[186:189], v[44:47]
	v_mfma_f32_16x16x32_bf16 v[40:43], v[154:157], v[186:189], v[40:43]
	v_mfma_f32_16x16x32_bf16 v[28:31], v[142:145], v[194:197], v[28:31]
	v_mfma_f32_16x16x32_bf16 v[24:27], v[154:157], v[194:197], v[24:27]
	v_mfma_f32_16x16x32_bf16 v[12:15], v[142:145], v[216:219], v[12:15]
	v_mfma_f32_16x16x32_bf16 v[8:11], v[154:157], v[216:219], v[8:11]
	s_setprio 0
	s_setprio 1
	v_mfma_f32_16x16x32_bf16 v[52:55], v[158:161], v[174:177], 0
	v_mfma_f32_16x16x32_bf16 v[48:51], v[166:169], v[174:177], 0
	v_mfma_f32_16x16x32_bf16 v[36:39], v[158:161], v[182:185], 0
	v_mfma_f32_16x16x32_bf16 v[32:35], v[166:169], v[182:185], 0
	v_mfma_f32_16x16x32_bf16 v[20:23], v[158:161], v[190:193], 0
	v_mfma_f32_16x16x32_bf16 v[16:19], v[166:169], v[190:193], 0
	v_mfma_f32_16x16x32_bf16 v[4:7], v[158:161], v[212:215], 0
	v_mfma_f32_16x16x32_bf16 v[0:3], v[166:169], v[212:215], 0
	v_mfma_f32_16x16x32_bf16 v[52:55], v[162:165], v[178:181], v[52:55]
	v_mfma_f32_16x16x32_bf16 v[48:51], v[170:173], v[178:181], v[48:51]
	v_mfma_f32_16x16x32_bf16 v[36:39], v[162:165], v[186:189], v[36:39]
	v_mfma_f32_16x16x32_bf16 v[32:35], v[170:173], v[186:189], v[32:35]
	v_mfma_f32_16x16x32_bf16 v[20:23], v[162:165], v[194:197], v[20:23]
	v_mfma_f32_16x16x32_bf16 v[16:19], v[170:173], v[194:197], v[16:19]
	v_mfma_f32_16x16x32_bf16 v[4:7], v[162:165], v[216:219], v[4:7]
	v_mfma_f32_16x16x32_bf16 v[0:3], v[170:173], v[216:219], v[0:3]
	s_setprio 0
	s_barrier
	s_add_i32 s59, 0, 0x18000
	s_add_i32 s63, 0, 0x1c000
	v_add_u32_e32 v154, s59, v147
	v_add_u32_e32 v170, s63, v147
	ds_read_b128 v[138:141], v154
	ds_read_b128 v[142:145], v154 offset:1024
	ds_read_b128 v[150:153], v154 offset:2048
	ds_read_b128 v[154:157], v154 offset:3072
	ds_read_b128 v[158:161], v170
	ds_read_b128 v[162:165], v170 offset:1024
	ds_read_b128 v[166:169], v170 offset:2048
	ds_read_b128 v[170:173], v170 offset:3072
	s_add_u32 s0, s38, 0x80000
	s_addc_u32 s1, s39, 0
	s_mov_b32 m0, s46
	v_lshl_add_u64 v[228:229], s[0:1], 0, v[132:133]
	ds_read_b128 v[174:177], v149 offset:32768
	ds_read_b128 v[178:181], v149 offset:33792
	ds_read_b128 v[182:185], v149 offset:34816
	ds_read_b128 v[186:189], v149 offset:35840
	ds_read_b128 v[190:193], v149 offset:36864
	ds_read_b128 v[194:197], v149 offset:37888
	ds_read_b128 v[212:215], v149 offset:38912
	ds_read_b128 v[216:219], v149 offset:39936
	global_load_lds_dwordx4 v[228:229], off
	v_lshl_add_u64 v[228:229], s[0:1], 0, v[130:131]
	s_mov_b32 m0, s47
	s_nop 0
	global_load_lds_dwordx4 v[228:229], off
	s_waitcnt vmcnt(8)
	s_waitcnt lgkmcnt(0)
	s_barrier
	s_setprio 1
	s_waitcnt lgkmcnt(0)
	v_mfma_f32_16x16x32_bf16 v[124:127], v[138:141], v[174:177], v[124:127]
	v_mfma_f32_16x16x32_bf16 v[120:123], v[150:153], v[174:177], v[120:123]
	v_mfma_f32_16x16x32_bf16 v[108:111], v[138:141], v[182:185], v[108:111]
	v_mfma_f32_16x16x32_bf16 v[104:107], v[150:153], v[182:185], v[104:107]
	v_mfma_f32_16x16x32_bf16 v[92:95], v[138:141], v[190:193], v[92:95]
	v_mfma_f32_16x16x32_bf16 v[88:91], v[150:153], v[190:193], v[88:91]
	v_mfma_f32_16x16x32_bf16 v[76:79], v[138:141], v[212:215], v[76:79]
	v_mfma_f32_16x16x32_bf16 v[72:75], v[150:153], v[212:215], v[72:75]
	v_mfma_f32_16x16x32_bf16 v[124:127], v[142:145], v[178:181], v[124:127]
	v_mfma_f32_16x16x32_bf16 v[120:123], v[154:157], v[178:181], v[120:123]
	v_mfma_f32_16x16x32_bf16 v[108:111], v[142:145], v[186:189], v[108:111]
	v_mfma_f32_16x16x32_bf16 v[104:107], v[154:157], v[186:189], v[104:107]
	v_mfma_f32_16x16x32_bf16 v[92:95], v[142:145], v[194:197], v[92:95]
	v_mfma_f32_16x16x32_bf16 v[88:91], v[154:157], v[194:197], v[88:91]
	v_mfma_f32_16x16x32_bf16 v[76:79], v[142:145], v[216:219], v[76:79]
	v_mfma_f32_16x16x32_bf16 v[72:75], v[154:157], v[216:219], v[72:75]
	s_setprio 0
	s_setprio 1
	v_mfma_f32_16x16x32_bf16 v[116:119], v[158:161], v[174:177], v[116:119]
	v_mfma_f32_16x16x32_bf16 v[112:115], v[166:169], v[174:177], v[112:115]
	v_mfma_f32_16x16x32_bf16 v[100:103], v[158:161], v[182:185], v[100:103]
	v_mfma_f32_16x16x32_bf16 v[96:99], v[166:169], v[182:185], v[96:99]
	v_mfma_f32_16x16x32_bf16 v[84:87], v[158:161], v[190:193], v[84:87]
	v_mfma_f32_16x16x32_bf16 v[80:83], v[166:169], v[190:193], v[80:83]
	v_mfma_f32_16x16x32_bf16 v[68:71], v[158:161], v[212:215], v[68:71]
	v_mfma_f32_16x16x32_bf16 v[64:67], v[166:169], v[212:215], v[64:67]
	v_mfma_f32_16x16x32_bf16 v[116:119], v[162:165], v[178:181], v[116:119]
	v_mfma_f32_16x16x32_bf16 v[112:115], v[170:173], v[178:181], v[112:115]
	v_mfma_f32_16x16x32_bf16 v[100:103], v[162:165], v[186:189], v[100:103]
	v_mfma_f32_16x16x32_bf16 v[96:99], v[170:173], v[186:189], v[96:99]
	v_mfma_f32_16x16x32_bf16 v[84:87], v[162:165], v[194:197], v[84:87]
	v_mfma_f32_16x16x32_bf16 v[80:83], v[170:173], v[194:197], v[80:83]
	v_mfma_f32_16x16x32_bf16 v[68:71], v[162:165], v[216:219], v[68:71]
	v_mfma_f32_16x16x32_bf16 v[64:67], v[170:173], v[216:219], v[64:67]
	s_setprio 0
	s_barrier
	s_add_i32 s0, s59, s42
	v_lshl_add_u64 v[220:221], v[220:221], 0, s[54:55]
	s_mov_b32 m0, s0
	ds_read_b128 v[174:177], v149 offset:49152
	ds_read_b128 v[178:181], v149 offset:50176
	ds_read_b128 v[182:185], v149 offset:51200
	ds_read_b128 v[186:189], v149 offset:52224
	ds_read_b128 v[190:193], v149 offset:53248
	ds_read_b128 v[194:197], v149 offset:54272
	ds_read_b128 v[212:215], v149 offset:55296
	ds_read_b128 v[216:219], v149 offset:56320
	global_load_lds_dwordx4 v[220:221], off
	s_add_i32 m0, s0, 0x2000
	s_add_u32 s0, s36, 0x80080
	v_lshl_add_u64 v[220:221], v[222:223], 0, s[54:55]
	s_addc_u32 s1, s37, 0
	s_add_i32 s36, s63, s42
	global_load_lds_dwordx4 v[220:221], off
	v_lshl_add_u64 v[220:221], s[0:1], 0, v[198:199]
	s_mov_b32 m0, s36
	s_nop 0
	global_load_lds_dwordx4 v[220:221], off
	v_lshl_add_u64 v[220:221], s[0:1], 0, v[128:129]
	s_add_i32 m0, s36, 0x2000
	s_nop 0
	global_load_lds_dwordx4 v[220:221], off
	v_lshl_add_u64 v[220:221], v[224:225], 0, s[54:55]
	s_mov_b32 m0, s49
	s_nop 0
	global_load_lds_dwordx4 v[220:221], off
	v_lshl_add_u64 v[220:221], v[226:227], 0, s[54:55]
	s_mov_b32 m0, s50
	s_nop 0
	global_load_lds_dwordx4 v[220:221], off
	s_waitcnt vmcnt(8)
	s_waitcnt lgkmcnt(0)
	s_barrier
	s_setprio 1
	s_waitcnt lgkmcnt(0)
	v_mfma_f32_16x16x32_bf16 v[60:63], v[138:141], v[174:177], v[60:63]
	v_mfma_f32_16x16x32_bf16 v[56:59], v[150:153], v[174:177], v[56:59]
	v_mfma_f32_16x16x32_bf16 v[44:47], v[138:141], v[182:185], v[44:47]
	v_mfma_f32_16x16x32_bf16 v[40:43], v[150:153], v[182:185], v[40:43]
	v_mfma_f32_16x16x32_bf16 v[28:31], v[138:141], v[190:193], v[28:31]
	v_mfma_f32_16x16x32_bf16 v[24:27], v[150:153], v[190:193], v[24:27]
	v_mfma_f32_16x16x32_bf16 v[12:15], v[138:141], v[212:215], v[12:15]
	v_mfma_f32_16x16x32_bf16 v[8:11], v[150:153], v[212:215], v[8:11]
	v_mfma_f32_16x16x32_bf16 v[60:63], v[142:145], v[178:181], v[60:63]
	v_mfma_f32_16x16x32_bf16 v[56:59], v[154:157], v[178:181], v[56:59]
	v_mfma_f32_16x16x32_bf16 v[44:47], v[142:145], v[186:189], v[44:47]
	v_mfma_f32_16x16x32_bf16 v[40:43], v[154:157], v[186:189], v[40:43]
	v_mfma_f32_16x16x32_bf16 v[28:31], v[142:145], v[194:197], v[28:31]
	v_mfma_f32_16x16x32_bf16 v[24:27], v[154:157], v[194:197], v[24:27]
	v_mfma_f32_16x16x32_bf16 v[12:15], v[142:145], v[216:219], v[12:15]
	v_mfma_f32_16x16x32_bf16 v[8:11], v[154:157], v[216:219], v[8:11]
	s_setprio 0
	s_setprio 1
	v_mfma_f32_16x16x32_bf16 v[52:55], v[158:161], v[174:177], v[52:55]
	v_mfma_f32_16x16x32_bf16 v[48:51], v[166:169], v[174:177], v[48:51]
	v_mfma_f32_16x16x32_bf16 v[36:39], v[158:161], v[182:185], v[36:39]
	v_mfma_f32_16x16x32_bf16 v[32:35], v[166:169], v[182:185], v[32:35]
	v_mfma_f32_16x16x32_bf16 v[20:23], v[158:161], v[190:193], v[20:23]
	v_mfma_f32_16x16x32_bf16 v[16:19], v[166:169], v[190:193], v[16:19]
	v_mfma_f32_16x16x32_bf16 v[4:7], v[158:161], v[212:215], v[4:7]
	v_mfma_f32_16x16x32_bf16 v[0:3], v[166:169], v[212:215], v[0:3]
	v_mfma_f32_16x16x32_bf16 v[52:55], v[162:165], v[178:181], v[52:55]
	v_mfma_f32_16x16x32_bf16 v[48:51], v[170:173], v[178:181], v[48:51]
	v_mfma_f32_16x16x32_bf16 v[36:39], v[162:165], v[186:189], v[36:39]
	v_mfma_f32_16x16x32_bf16 v[32:35], v[170:173], v[186:189], v[32:35]
	v_mfma_f32_16x16x32_bf16 v[20:23], v[162:165], v[194:197], v[20:23]
	v_mfma_f32_16x16x32_bf16 v[16:19], v[170:173], v[194:197], v[16:19]
	v_mfma_f32_16x16x32_bf16 v[4:7], v[162:165], v[216:219], v[4:7]
	v_mfma_f32_16x16x32_bf16 v[0:3], v[170:173], v[216:219], v[0:3]
	s_setprio 0
	s_barrier
	s_add_i32 s79, s79, 2
	s_add_u32 s30, s30, 0x100
	s_addc_u32 s31, s31, 0
	s_add_u32 s35, s35, 0x100
	s_addc_u32 s69, s69, 0

.LBB0_479:
	s_add_u32 s16, s70, 0xa140000
	s_addc_u32 s17, s71, 0
	s_lshl_b32 s6, s6, 5
	s_and_b32 s9, s6, 0x60
	s_add_i32 m0, s45, 0x18000
	v_lshl_add_u64 v[6:7], v[6:7], 0, s[54:55]
	s_lshl_b32 s8, s0, 13
	s_lshl_b32 s10, s9, 7
	s_waitcnt vmcnt(2)
	s_barrier
	global_load_lds_dwordx4 v[6:7], off
	v_lshl_add_u64 v[4:5], v[4:5], 0, s[54:55]
	s_add_i32 m0, s45, 0x1a000
	s_add_i32 s49, s45, 0x8000
	s_add_i32 s50, s45, 0xa000
	global_load_lds_dwordx4 v[4:5], off
	v_lshl_add_u64 v[0:1], v[0:1], 0, s[54:55]
	s_mov_b32 m0, s49
	s_add_u32 s6, s30, 0x160080
	global_load_lds_dwordx4 v[0:1], off
	v_lshl_add_u64 v[0:1], v[2:3], 0, s[54:55]
	s_mov_b32 m0, s50
	s_addc_u32 s7, s31, 0
	global_load_lds_dwordx4 v[0:1], off
	s_add_i32 m0, s45, 0x1c000
	v_lshl_add_u64 v[0:1], s[6:7], 0, v[198:199]
	global_load_lds_dwordx4 v[0:1], off
	v_lshl_add_u64 v[0:1], s[6:7], 0, v[176:177]
	s_add_i32 m0, s45, 0x1e000
	s_waitcnt lgkmcnt(0)
	s_ashr_i32 s51, s27, 31
	global_load_lds_dwordx4 v[0:1], off
	v_bfe_u32 v1, v8, 4, 2
	v_and_b32_e32 v0, 15, v8
	v_lshlrev_b32_e32 v2, 4, v1
	v_lshl_or_b32 v194, s0, 6, v0
	v_lshl_or_b32 v0, v0, 6, v2
	v_lshlrev_b32_e32 v2, 2, v8
	v_and_b32_e32 v2, 32, v2
	v_bitop3_b32 v3, v0, s8, v2 bitop3:0xde
	s_movk_i32 s8, 0x1600
	v_bitop3_b32 v195, s10, v0, v2 bitop3:0xf6
	v_cmp_eq_u32_e64 s[6:7], 0, v1
	v_lshl_or_b32 v196, v1, 2, s9
	v_lshrrev_b32_e32 v1, 1, v9
	v_mul_lo_u32 v0, v11, s8
	s_mov_b32 s9, 0x16000
	s_cmpk_lt_u32 s1, 0x100
	v_mad_u64_u32 v[0:1], s[0:1], v1, s9, v[0:1]
	v_or_b32_e32 v0, v0, v10
	v_add_lshl_u32 v0, v0, v12, 1
	v_mov_b32_e32 v1, v199
	s_mov_b64 s[10:11], 0x160080
	v_lshl_add_u64 v[178:179], v[0:1], 0, s[10:11]
	v_lshrrev_b32_e32 v1, 1, v13
	v_mul_lo_u32 v0, v15, s8
	v_mad_u64_u32 v[0:1], s[0:1], v1, s9, v[0:1]
	s_waitcnt vmcnt(0)
	v_or_b32_e32 v0, v0, v14
	v_add_lshl_u32 v0, v0, v16, 1
	v_mov_b32_e32 v1, v199
	s_cselect_b64 s[18:19], -1, 0
	s_mov_b32 s52, 0
	v_lshl_add_u64 v[180:181], v[0:1], 0, s[10:11]
	v_add_u32_e32 v197, 0, v3
	s_barrier
	s_branch .LBB0_482

.LBB0_492:
	s_add_u32 s34, s30, 0x100
	s_addc_u32 s35, s31, 0
	s_mov_b32 s81, -2
	s_waitcnt lgkmcnt(0)
	s_add_u32 s30, s28, 0x100
	s_addc_u32 s31, s29, 0
	s_add_i32 s0, 0, 0x10000
	s_cmpk_eq_i32 s81, 0x54
	s_cselect_b32 s39, s11, s31
	s_cselect_b32 s38, s10, s30
	s_cselect_b32 s37, s21, s35
	s_cselect_b32 s36, s20, s34
	s_add_i32 s59, 0, 0x14000
	v_add_u32_e32 v140, s0, v195
	v_add_u32_e32 v156, s59, v195
	ds_read_b128 v[120:123], v140
	ds_read_b128 v[124:127], v140 offset:1024
	ds_read_b128 v[128:131], v140 offset:2048
	ds_read_b128 v[140:143], v140 offset:3072
	ds_read_b128 v[144:147], v156
	ds_read_b128 v[148:151], v156 offset:1024
	ds_read_b128 v[152:155], v156 offset:2048
	ds_read_b128 v[156:159], v156 offset:3072
	v_lshl_add_u64 v[216:217], s[28:29], 0, v[178:179]
	s_add_i32 m0, s45, 0xc000
	ds_read_b128 v[160:163], v197
	ds_read_b128 v[164:167], v197 offset:1024
	ds_read_b128 v[168:171], v197 offset:2048
	ds_read_b128 v[172:175], v197 offset:3072
	ds_read_b128 v[182:185], v197 offset:4096
	ds_read_b128 v[186:189], v197 offset:5120
	ds_read_b128 v[190:193], v197 offset:6144
	ds_read_b128 v[212:215], v197 offset:7168
	global_load_lds_dwordx4 v[216:217], off
	v_lshl_add_u64 v[216:217], s[28:29], 0, v[180:181]
	s_add_i32 m0, s45, 0xe000
	s_nop 0
	global_load_lds_dwordx4 v[216:217], off
	s_waitcnt vmcnt(63)
	s_waitcnt lgkmcnt(0)
	s_barrier
	s_setprio 1
	s_waitcnt lgkmcnt(0)
	v_mfma_f32_16x16x32_bf16 v[136:139], v[120:123], v[160:163], 0
	v_mfma_f32_16x16x32_bf16 v[132:135], v[128:131], v[160:163], 0
	v_mfma_f32_16x16x32_bf16 v[108:111], v[120:123], v[168:171], 0
	v_mfma_f32_16x16x32_bf16 v[104:107], v[128:131], v[168:171], 0
	v_mfma_f32_16x16x32_bf16 v[92:95], v[120:123], v[182:185], 0
	v_mfma_f32_16x16x32_bf16 v[88:91], v[128:131], v[182:185], 0
	v_mfma_f32_16x16x32_bf16 v[76:79], v[120:123], v[190:193], 0
	v_mfma_f32_16x16x32_bf16 v[72:75], v[128:131], v[190:193], 0
	v_mfma_f32_16x16x32_bf16 v[136:139], v[124:127], v[164:167], v[136:139]
	v_mfma_f32_16x16x32_bf16 v[132:135], v[140:143], v[164:167], v[132:135]
	v_mfma_f32_16x16x32_bf16 v[108:111], v[124:127], v[172:175], v[108:111]
	v_mfma_f32_16x16x32_bf16 v[104:107], v[140:143], v[172:175], v[104:107]
	v_mfma_f32_16x16x32_bf16 v[92:95], v[124:127], v[186:189], v[92:95]
	v_mfma_f32_16x16x32_bf16 v[88:91], v[140:143], v[186:189], v[88:91]
	v_mfma_f32_16x16x32_bf16 v[76:79], v[124:127], v[212:215], v[76:79]
	v_mfma_f32_16x16x32_bf16 v[72:75], v[140:143], v[212:215], v[72:75]
	s_setprio 0
	s_setprio 1
	v_mfma_f32_16x16x32_bf16 v[116:119], v[144:147], v[160:163], 0
	v_mfma_f32_16x16x32_bf16 v[112:115], v[152:155], v[160:163], 0
	v_mfma_f32_16x16x32_bf16 v[100:103], v[144:147], v[168:171], 0
	v_mfma_f32_16x16x32_bf16 v[96:99], v[152:155], v[168:171], 0
	v_mfma_f32_16x16x32_bf16 v[84:87], v[144:147], v[182:185], 0
	v_mfma_f32_16x16x32_bf16 v[80:83], v[152:155], v[182:185], 0
	v_mfma_f32_16x16x32_bf16 v[68:71], v[144:147], v[190:193], 0
	v_mfma_f32_16x16x32_bf16 v[64:67], v[152:155], v[190:193], 0
	v_mfma_f32_16x16x32_bf16 v[116:119], v[148:151], v[164:167], v[116:119]
	v_mfma_f32_16x16x32_bf16 v[112:115], v[156:159], v[164:167], v[112:115]
	v_mfma_f32_16x16x32_bf16 v[100:103], v[148:151], v[172:175], v[100:103]
	v_mfma_f32_16x16x32_bf16 v[96:99], v[156:159], v[172:175], v[96:99]
	v_mfma_f32_16x16x32_bf16 v[84:87], v[148:151], v[186:189], v[84:87]
	v_mfma_f32_16x16x32_bf16 v[80:83], v[156:159], v[186:189], v[80:83]
	v_mfma_f32_16x16x32_bf16 v[68:71], v[148:151], v[212:215], v[68:71]
	v_mfma_f32_16x16x32_bf16 v[64:67], v[156:159], v[212:215], v[64:67]
	s_setprio 0
	s_barrier
	s_add_i32 s0, s0, s44
	v_lshl_add_u64 v[216:217], s[36:37], 0, v[198:199]
	s_mov_b32 m0, s0
	ds_read_b128 v[160:163], v197 offset:16384
	ds_read_b128 v[164:167], v197 offset:17408
	ds_read_b128 v[168:171], v197 offset:18432
	ds_read_b128 v[172:175], v197 offset:19456
	ds_read_b128 v[182:185], v197 offset:20480
	ds_read_b128 v[186:189], v197 offset:21504
	ds_read_b128 v[190:193], v197 offset:22528
	ds_read_b128 v[212:215], v197 offset:23552
	global_load_lds_dwordx4 v[216:217], off
	s_add_i32 m0, s0, 0x2000
	s_add_u32 s0, s36, 0x160000
	v_lshl_add_u64 v[218:219], s[36:37], 0, v[176:177]
	s_addc_u32 s1, s37, 0
	s_add_i32 s28, s59, s44
	global_load_lds_dwordx4 v[218:219], off
	v_lshl_add_u64 v[220:221], s[0:1], 0, v[198:199]
	s_mov_b32 m0, s28
	v_lshl_add_u64 v[222:223], s[38:39], 0, v[176:177]
	global_load_lds_dwordx4 v[220:221], off
	v_lshl_add_u64 v[220:221], s[0:1], 0, v[176:177]
	s_add_i32 m0, s28, 0x2000
	s_nop 0
	global_load_lds_dwordx4 v[220:221], off
	v_lshl_add_u64 v[220:221], s[38:39], 0, v[198:199]
	s_mov_b32 m0, s45
	s_nop 0
	global_load_lds_dwordx4 v[220:221], off
	s_mov_b32 m0, s46
	s_nop 0
	global_load_lds_dwordx4 v[222:223], off
	s_waitcnt vmcnt(63)
	s_waitcnt lgkmcnt(0)
	s_barrier
	s_setprio 1
	s_waitcnt lgkmcnt(0)
	v_mfma_f32_16x16x32_bf16 v[60:63], v[120:123], v[160:163], 0
	v_mfma_f32_16x16x32_bf16 v[56:59], v[128:131], v[160:163], 0
	v_mfma_f32_16x16x32_bf16 v[44:47], v[120:123], v[168:171], 0
	v_mfma_f32_16x16x32_bf16 v[40:43], v[128:131], v[168:171], 0
	v_mfma_f32_16x16x32_bf16 v[28:31], v[120:123], v[182:185], 0
	v_mfma_f32_16x16x32_bf16 v[24:27], v[128:131], v[182:185], 0
	v_mfma_f32_16x16x32_bf16 v[12:15], v[120:123], v[190:193], 0
	v_mfma_f32_16x16x32_bf16 v[8:11], v[128:131], v[190:193], 0
	v_mfma_f32_16x16x32_bf16 v[60:63], v[124:127], v[164:167], v[60:63]
	v_mfma_f32_16x16x32_bf16 v[56:59], v[140:143], v[164:167], v[56:59]
	v_mfma_f32_16x16x32_bf16 v[44:47], v[124:127], v[172:175], v[44:47]
	v_mfma_f32_16x16x32_bf16 v[40:43], v[140:143], v[172:175], v[40:43]
	v_mfma_f32_16x16x32_bf16 v[28:31], v[124:127], v[186:189], v[28:31]
	v_mfma_f32_16x16x32_bf16 v[24:27], v[140:143], v[186:189], v[24:27]
	v_mfma_f32_16x16x32_bf16 v[12:15], v[124:127], v[212:215], v[12:15]
	v_mfma_f32_16x16x32_bf16 v[8:11], v[140:143], v[212:215], v[8:11]
	s_setprio 0
	s_setprio 1
	v_mfma_f32_16x16x32_bf16 v[52:55], v[144:147], v[160:163], 0
	v_mfma_f32_16x16x32_bf16 v[48:51], v[152:155], v[160:163], 0
	v_mfma_f32_16x16x32_bf16 v[36:39], v[144:147], v[168:171], 0
	v_mfma_f32_16x16x32_bf16 v[32:35], v[152:155], v[168:171], 0
	v_mfma_f32_16x16x32_bf16 v[20:23], v[144:147], v[182:185], 0
	v_mfma_f32_16x16x32_bf16 v[16:19], v[152:155], v[182:185], 0
	v_mfma_f32_16x16x32_bf16 v[4:7], v[144:147], v[190:193], 0
	v_mfma_f32_16x16x32_bf16 v[0:3], v[152:155], v[190:193], 0
	v_mfma_f32_16x16x32_bf16 v[52:55], v[148:151], v[164:167], v[52:55]
	v_mfma_f32_16x16x32_bf16 v[48:51], v[156:159], v[164:167], v[48:51]
	v_mfma_f32_16x16x32_bf16 v[36:39], v[148:151], v[172:175], v[36:39]
	v_mfma_f32_16x16x32_bf16 v[32:35], v[156:159], v[172:175], v[32:35]
	v_mfma_f32_16x16x32_bf16 v[20:23], v[148:151], v[186:189], v[20:23]
	v_mfma_f32_16x16x32_bf16 v[16:19], v[156:159], v[186:189], v[16:19]
	v_mfma_f32_16x16x32_bf16 v[4:7], v[148:151], v[212:215], v[4:7]
	v_mfma_f32_16x16x32_bf16 v[0:3], v[156:159], v[212:215], v[0:3]
	s_setprio 0
	s_barrier
	s_add_i32 s28, 0, 0x18000
	s_add_i32 s29, 0, 0x1c000
	v_add_u32_e32 v140, s28, v195
	v_add_u32_e32 v156, s29, v195
	ds_read_b128 v[120:123], v140
	ds_read_b128 v[124:127], v140 offset:1024
	ds_read_b128 v[128:131], v140 offset:2048
	ds_read_b128 v[140:143], v140 offset:3072
	ds_read_b128 v[144:147], v156
	ds_read_b128 v[148:151], v156 offset:1024
	ds_read_b128 v[152:155], v156 offset:2048
	ds_read_b128 v[156:159], v156 offset:3072
	s_add_u32 s0, s38, 0x160000
	s_addc_u32 s1, s39, 0
	s_mov_b32 m0, s47
	v_lshl_add_u64 v[224:225], s[0:1], 0, v[198:199]
	ds_read_b128 v[160:163], v197 offset:32768
	ds_read_b128 v[164:167], v197 offset:33792
	ds_read_b128 v[168:171], v197 offset:34816
	ds_read_b128 v[172:175], v197 offset:35840
	ds_read_b128 v[182:185], v197 offset:36864
	ds_read_b128 v[186:189], v197 offset:37888
	ds_read_b128 v[190:193], v197 offset:38912
	ds_read_b128 v[212:215], v197 offset:39936
	global_load_lds_dwordx4 v[224:225], off
	v_lshl_add_u64 v[224:225], s[0:1], 0, v[176:177]
	s_mov_b32 m0, s48
	s_nop 0
	global_load_lds_dwordx4 v[224:225], off
	s_waitcnt vmcnt(8)
	s_waitcnt lgkmcnt(0)
	s_barrier
	s_setprio 1
	s_waitcnt lgkmcnt(0)
	v_mfma_f32_16x16x32_bf16 v[136:139], v[120:123], v[160:163], v[136:139]
	v_mfma_f32_16x16x32_bf16 v[132:135], v[128:131], v[160:163], v[132:135]
	v_mfma_f32_16x16x32_bf16 v[108:111], v[120:123], v[168:171], v[108:111]
	v_mfma_f32_16x16x32_bf16 v[104:107], v[128:131], v[168:171], v[104:107]
	v_mfma_f32_16x16x32_bf16 v[92:95], v[120:123], v[182:185], v[92:95]
	v_mfma_f32_16x16x32_bf16 v[88:91], v[128:131], v[182:185], v[88:91]
	v_mfma_f32_16x16x32_bf16 v[76:79], v[120:123], v[190:193], v[76:79]
	v_mfma_f32_16x16x32_bf16 v[72:75], v[128:131], v[190:193], v[72:75]
	v_mfma_f32_16x16x32_bf16 v[136:139], v[124:127], v[164:167], v[136:139]
	v_mfma_f32_16x16x32_bf16 v[132:135], v[140:143], v[164:167], v[132:135]
	v_mfma_f32_16x16x32_bf16 v[108:111], v[124:127], v[172:175], v[108:111]
	v_mfma_f32_16x16x32_bf16 v[104:107], v[140:143], v[172:175], v[104:107]
	v_mfma_f32_16x16x32_bf16 v[92:95], v[124:127], v[186:189], v[92:95]
	v_mfma_f32_16x16x32_bf16 v[88:91], v[140:143], v[186:189], v[88:91]
	v_mfma_f32_16x16x32_bf16 v[76:79], v[124:127], v[212:215], v[76:79]
	v_mfma_f32_16x16x32_bf16 v[72:75], v[140:143], v[212:215], v[72:75]
	s_setprio 0
	s_setprio 1
	v_mfma_f32_16x16x32_bf16 v[116:119], v[144:147], v[160:163], v[116:119]
	v_mfma_f32_16x16x32_bf16 v[112:115], v[152:155], v[160:163], v[112:115]
	v_mfma_f32_16x16x32_bf16 v[100:103], v[144:147], v[168:171], v[100:103]
	v_mfma_f32_16x16x32_bf16 v[96:99], v[152:155], v[168:171], v[96:99]
	v_mfma_f32_16x16x32_bf16 v[84:87], v[144:147], v[182:185], v[84:87]
	v_mfma_f32_16x16x32_bf16 v[80:83], v[152:155], v[182:185], v[80:83]
	v_mfma_f32_16x16x32_bf16 v[68:71], v[144:147], v[190:193], v[68:71]
	v_mfma_f32_16x16x32_bf16 v[64:67], v[152:155], v[190:193], v[64:67]
	v_mfma_f32_16x16x32_bf16 v[116:119], v[148:151], v[164:167], v[116:119]
	v_mfma_f32_16x16x32_bf16 v[112:115], v[156:159], v[164:167], v[112:115]
	v_mfma_f32_16x16x32_bf16 v[100:103], v[148:151], v[172:175], v[100:103]
	v_mfma_f32_16x16x32_bf16 v[96:99], v[156:159], v[172:175], v[96:99]
	v_mfma_f32_16x16x32_bf16 v[84:87], v[148:151], v[186:189], v[84:87]
	v_mfma_f32_16x16x32_bf16 v[80:83], v[156:159], v[186:189], v[80:83]
	v_mfma_f32_16x16x32_bf16 v[68:71], v[148:151], v[212:215], v[68:71]
	v_mfma_f32_16x16x32_bf16 v[64:67], v[156:159], v[212:215], v[64:67]
	s_setprio 0
	s_barrier
	s_add_i32 s0, s28, s44
	v_lshl_add_u64 v[216:217], v[216:217], 0, s[54:55]
	s_mov_b32 m0, s0
	ds_read_b128 v[160:163], v197 offset:49152
	ds_read_b128 v[164:167], v197 offset:50176
	ds_read_b128 v[168:171], v197 offset:51200
	ds_read_b128 v[172:175], v197 offset:52224
	ds_read_b128 v[182:185], v197 offset:53248
	ds_read_b128 v[186:189], v197 offset:54272
	ds_read_b128 v[190:193], v197 offset:55296
	ds_read_b128 v[212:215], v197 offset:56320
	global_load_lds_dwordx4 v[216:217], off
	s_add_i32 m0, s0, 0x2000
	s_add_u32 s0, s36, 0x160080
	v_lshl_add_u64 v[216:217], v[218:219], 0, s[54:55]
	s_addc_u32 s1, s37, 0
	s_add_i32 s28, s29, s44
	global_load_lds_dwordx4 v[216:217], off
	v_lshl_add_u64 v[216:217], s[0:1], 0, v[198:199]
	s_mov_b32 m0, s28
	s_nop 0
	global_load_lds_dwordx4 v[216:217], off
	v_lshl_add_u64 v[216:217], s[0:1], 0, v[176:177]
	s_add_i32 m0, s28, 0x2000
	s_nop 0
	global_load_lds_dwordx4 v[216:217], off
	v_lshl_add_u64 v[216:217], v[220:221], 0, s[54:55]
	s_mov_b32 m0, s49
	s_nop 0
	global_load_lds_dwordx4 v[216:217], off
	v_lshl_add_u64 v[216:217], v[222:223], 0, s[54:55]
	s_mov_b32 m0, s50
	s_nop 0
	global_load_lds_dwordx4 v[216:217], off
	s_waitcnt vmcnt(8)
	s_waitcnt lgkmcnt(0)
	s_barrier
	s_setprio 1
	s_waitcnt lgkmcnt(0)
	v_mfma_f32_16x16x32_bf16 v[60:63], v[120:123], v[160:163], v[60:63]
	v_mfma_f32_16x16x32_bf16 v[56:59], v[128:131], v[160:163], v[56:59]
	v_mfma_f32_16x16x32_bf16 v[44:47], v[120:123], v[168:171], v[44:47]
	v_mfma_f32_16x16x32_bf16 v[40:43], v[128:131], v[168:171], v[40:43]
	v_mfma_f32_16x16x32_bf16 v[28:31], v[120:123], v[182:185], v[28:31]
	v_mfma_f32_16x16x32_bf16 v[24:27], v[128:131], v[182:185], v[24:27]
	v_mfma_f32_16x16x32_bf16 v[12:15], v[120:123], v[190:193], v[12:15]
	v_mfma_f32_16x16x32_bf16 v[8:11], v[128:131], v[190:193], v[8:11]
	v_mfma_f32_16x16x32_bf16 v[60:63], v[124:127], v[164:167], v[60:63]
	v_mfma_f32_16x16x32_bf16 v[56:59], v[140:143], v[164:167], v[56:59]
	v_mfma_f32_16x16x32_bf16 v[44:47], v[124:127], v[172:175], v[44:47]
	v_mfma_f32_16x16x32_bf16 v[40:43], v[140:143], v[172:175], v[40:43]
	v_mfma_f32_16x16x32_bf16 v[28:31], v[124:127], v[186:189], v[28:31]
	v_mfma_f32_16x16x32_bf16 v[24:27], v[140:143], v[186:189], v[24:27]
	v_mfma_f32_16x16x32_bf16 v[12:15], v[124:127], v[212:215], v[12:15]
	v_mfma_f32_16x16x32_bf16 v[8:11], v[140:143], v[212:215], v[8:11]
	s_setprio 0
	s_setprio 1
	v_mfma_f32_16x16x32_bf16 v[52:55], v[144:147], v[160:163], v[52:55]
	v_mfma_f32_16x16x32_bf16 v[48:51], v[152:155], v[160:163], v[48:51]
	v_mfma_f32_16x16x32_bf16 v[36:39], v[144:147], v[168:171], v[36:39]
	v_mfma_f32_16x16x32_bf16 v[32:35], v[152:155], v[168:171], v[32:35]
	v_mfma_f32_16x16x32_bf16 v[20:23], v[144:147], v[182:185], v[20:23]
	v_mfma_f32_16x16x32_bf16 v[16:19], v[152:155], v[182:185], v[16:19]
	v_mfma_f32_16x16x32_bf16 v[4:7], v[144:147], v[190:193], v[4:7]
	v_mfma_f32_16x16x32_bf16 v[0:3], v[152:155], v[190:193], v[0:3]
	v_mfma_f32_16x16x32_bf16 v[52:55], v[148:151], v[164:167], v[52:55]
	v_mfma_f32_16x16x32_bf16 v[48:51], v[156:159], v[164:167], v[48:51]
	v_mfma_f32_16x16x32_bf16 v[36:39], v[148:151], v[172:175], v[36:39]
	v_mfma_f32_16x16x32_bf16 v[32:35], v[156:159], v[172:175], v[32:35]
	v_mfma_f32_16x16x32_bf16 v[20:23], v[148:151], v[186:189], v[20:23]
	v_mfma_f32_16x16x32_bf16 v[16:19], v[156:159], v[186:189], v[16:19]
	v_mfma_f32_16x16x32_bf16 v[4:7], v[148:151], v[212:215], v[4:7]
	v_mfma_f32_16x16x32_bf16 v[0:3], v[156:159], v[212:215], v[0:3]
	s_setprio 0
	s_barrier
	s_add_i32 s81, s81, 2
	s_add_u32 s34, s34, 0x100
	s_addc_u32 s35, s35, 0
	s_mov_b64 s[28:29], s[30:31]

.LBB0_522:
	s_add_u32 s10, s70, 0x12140000
	v_lshrrev_b32_e32 v16, 1, v14
	s_addc_u32 s11, s71, 0
	v_and_b32_e32 v16, 24, v16
	s_lshl_b32 s0, s0, 5
	s_sext_i32_i16 s29, s6
	v_and_b32_e32 v15, 15, v14
	v_lshlrev_b32_e32 v17, 1, v16
	v_lshlrev_b32_e32 v14, 2, v14
	s_and_b32 s6, s0, 0x60
	s_add_i32 m0, s42, 0x18000
	v_lshl_add_u64 v[6:7], v[6:7], 0, s[54:55]
	v_lshl_or_b32 v146, s1, 6, v15
	v_lshl_or_b32 v15, v15, 6, v17
	s_lshl_b32 s1, s1, 13
	v_and_b32_e32 v14, 32, v14
	s_lshl_b32 s0, s6, 7
	s_waitcnt vmcnt(2)
	s_barrier
	global_load_lds_dwordx4 v[6:7], off
	v_lshl_add_u64 v[4:5], v[4:5], 0, s[54:55]
	s_add_i32 m0, s42, 0x1a000
	s_add_i32 s47, s42, 0x8000
	s_add_i32 s48, s42, 0xa000
	v_bitop3_b32 v147, s0, v15, v14 bitop3:0xf6
	global_load_lds_dwordx4 v[4:5], off
	v_lshl_add_u64 v[0:1], v[0:1], 0, s[54:55]
	s_mov_b32 m0, s47
	s_add_u32 s0, s36, 0x80080
	v_bitop3_b32 v17, v15, s1, v14 bitop3:0xde
	global_load_lds_dwordx4 v[0:1], off
	v_lshl_add_u64 v[0:1], v[2:3], 0, s[54:55]
	s_mov_b32 m0, s48
	s_addc_u32 s1, s37, 0
	global_load_lds_dwordx4 v[0:1], off
	s_add_i32 m0, s42, 0x1c000
	v_lshl_add_u64 v[0:1], s[0:1], 0, v[198:199]
	global_load_lds_dwordx4 v[0:1], off
	v_lshl_add_u64 v[0:1], s[0:1], 0, v[128:129]
	s_add_i32 m0, s42, 0x1e000
	s_waitcnt lgkmcnt(0)
	s_ashr_i32 s49, s46, 31
	global_load_lds_dwordx4 v[0:1], off
	v_lshlrev_b32_e32 v0, 15, v12
	v_and_b32_e32 v0, 0xffff0000, v0
	v_lshl_add_u32 v0, v11, 12, v0
	v_and_b32_e32 v1, 1, v12
	v_lshl_or_b32 v0, v1, 6, v0
	v_lshl_add_u32 v134, v13, 1, v0
	v_lshlrev_b32_e32 v0, 15, v8
	v_and_b32_e32 v0, 0xffff0000, v0
	s_waitcnt vmcnt(0)
	v_lshl_add_u32 v0, v9, 12, v0
	v_and_b32_e32 v1, 1, v8
	s_cmpk_lt_u32 s7, 0x100
	v_lshl_or_b32 v0, v1, 6, v0
	s_cselect_b64 s[12:13], -1, 0
	v_or_b32_e32 v148, s6, v16
	v_mov_b32_e32 v135, v199
	v_lshl_add_u32 v136, v10, 1, v0
	v_mov_b32_e32 v137, v199
	s_mov_b32 s50, 0
	v_add_u32_e32 v149, 0, v17
	s_barrier
	s_branch .LBB0_525

.LBB0_527:
	s_ashr_i32 s17, s16, 31
	s_lshl_b64 s[0:1], s[16:17], 20
	s_add_u32 s18, s26, s0
	s_addc_u32 s19, s27, s1
	s_and_b64 s[0:1], s[6:7], exec
	s_cselect_b32 s17, s19, s31
	s_cselect_b32 s51, s18, s30
	s_ashr_i32 s15, s14, 31
	s_lshl_b64 s[0:1], s[14:15], 20
	s_add_u32 s20, s70, s0
	s_addc_u32 s21, s71, s1
	s_and_b64 s[0:1], s[6:7], exec
	s_cselect_b32 s15, s21, s37
	s_cselect_b32 s34, s20, s36
	s_add_u32 s30, s30, 0x80080
	s_addc_u32 s31, s31, 0
	s_add_u32 s35, s36, 0x100
	s_addc_u32 s52, s37, 0
	s_mov_b32 s61, -2
	s_add_u32 s0, s30, 0xfff80080
	s_addc_u32 s1, s31, -1
	s_add_i32 s59, 0, 0x10000
	s_cmp_eq_u32 s61, 28
	s_cselect_b32 s39, s17, s1
	s_cselect_b32 s38, s51, s0
	s_cselect_b32 s37, s15, s52
	s_cselect_b32 s36, s34, s35
	s_add_i32 s63, 0, 0x14000
	v_add_u32_e32 v154, s59, v147
	v_add_u32_e32 v170, s63, v147
	ds_read_b128 v[138:141], v154
	ds_read_b128 v[142:145], v154 offset:1024
	ds_read_b128 v[150:153], v154 offset:2048
	ds_read_b128 v[154:157], v154 offset:3072
	ds_read_b128 v[158:161], v170
	ds_read_b128 v[162:165], v170 offset:1024
	ds_read_b128 v[166:169], v170 offset:2048
	ds_read_b128 v[170:173], v170 offset:3072
	v_lshl_add_u64 v[220:221], s[30:31], 0, v[134:135]
	s_add_i32 m0, s42, 0xc000
	ds_read_b128 v[174:177], v149
	ds_read_b128 v[178:181], v149 offset:1024
	ds_read_b128 v[182:185], v149 offset:2048
	ds_read_b128 v[186:189], v149 offset:3072
	ds_read_b128 v[190:193], v149 offset:4096
	ds_read_b128 v[194:197], v149 offset:5120
	ds_read_b128 v[212:215], v149 offset:6144
	ds_read_b128 v[216:219], v149 offset:7168
	global_load_lds_dwordx4 v[220:221], off
	v_lshl_add_u64 v[220:221], s[30:31], 0, v[136:137]
	s_add_i32 m0, s42, 0xe000
	s_nop 0
	global_load_lds_dwordx4 v[220:221], off
	s_waitcnt vmcnt(63)
	s_waitcnt lgkmcnt(0)
	s_barrier
	s_setprio 1
	s_waitcnt lgkmcnt(0)
	v_mfma_f32_16x16x32_bf16 v[124:127], v[138:141], v[174:177], 0
	v_mfma_f32_16x16x32_bf16 v[116:119], v[150:153], v[174:177], 0
	v_mfma_f32_16x16x32_bf16 v[108:111], v[138:141], v[182:185], 0
	v_mfma_f32_16x16x32_bf16 v[96:99], v[150:153], v[182:185], 0
	v_mfma_f32_16x16x32_bf16 v[88:91], v[138:141], v[190:193], 0
	v_mfma_f32_16x16x32_bf16 v[80:83], v[150:153], v[190:193], 0
	v_mfma_f32_16x16x32_bf16 v[72:75], v[138:141], v[212:215], 0
	v_mfma_f32_16x16x32_bf16 v[64:67], v[150:153], v[212:215], 0
	v_mfma_f32_16x16x32_bf16 v[124:127], v[142:145], v[178:181], v[124:127]
	v_mfma_f32_16x16x32_bf16 v[116:119], v[154:157], v[178:181], v[116:119]
	v_mfma_f32_16x16x32_bf16 v[108:111], v[142:145], v[186:189], v[108:111]
	v_mfma_f32_16x16x32_bf16 v[96:99], v[154:157], v[186:189], v[96:99]
	v_mfma_f32_16x16x32_bf16 v[88:91], v[142:145], v[194:197], v[88:91]
	v_mfma_f32_16x16x32_bf16 v[80:83], v[154:157], v[194:197], v[80:83]
	v_mfma_f32_16x16x32_bf16 v[72:75], v[142:145], v[216:219], v[72:75]
	v_mfma_f32_16x16x32_bf16 v[64:67], v[154:157], v[216:219], v[64:67]
	s_setprio 0
	s_setprio 1
	v_mfma_f32_16x16x32_bf16 v[120:123], v[158:161], v[174:177], 0
	v_mfma_f32_16x16x32_bf16 v[112:115], v[166:169], v[174:177], 0
	v_mfma_f32_16x16x32_bf16 v[104:107], v[158:161], v[182:185], 0
	v_mfma_f32_16x16x32_bf16 v[100:103], v[166:169], v[182:185], 0
	v_mfma_f32_16x16x32_bf16 v[92:95], v[158:161], v[190:193], 0
	v_mfma_f32_16x16x32_bf16 v[84:87], v[166:169], v[190:193], 0
	v_mfma_f32_16x16x32_bf16 v[76:79], v[158:161], v[212:215], 0
	v_mfma_f32_16x16x32_bf16 v[68:71], v[166:169], v[212:215], 0
	v_mfma_f32_16x16x32_bf16 v[120:123], v[162:165], v[178:181], v[120:123]
	v_mfma_f32_16x16x32_bf16 v[112:115], v[170:173], v[178:181], v[112:115]
	v_mfma_f32_16x16x32_bf16 v[104:107], v[162:165], v[186:189], v[104:107]
	v_mfma_f32_16x16x32_bf16 v[100:103], v[170:173], v[186:189], v[100:103]
	v_mfma_f32_16x16x32_bf16 v[92:95], v[162:165], v[194:197], v[92:95]
	v_mfma_f32_16x16x32_bf16 v[84:87], v[170:173], v[194:197], v[84:87]
	v_mfma_f32_16x16x32_bf16 v[76:79], v[162:165], v[216:219], v[76:79]
	v_mfma_f32_16x16x32_bf16 v[68:71], v[170:173], v[216:219], v[68:71]
	s_setprio 0
	s_barrier
	s_add_i32 s0, s59, s40
	v_lshl_add_u64 v[220:221], s[36:37], 0, v[198:199]
	s_mov_b32 m0, s0
	ds_read_b128 v[174:177], v149 offset:16384
	ds_read_b128 v[178:181], v149 offset:17408
	ds_read_b128 v[182:185], v149 offset:18432
	ds_read_b128 v[186:189], v149 offset:19456
	ds_read_b128 v[190:193], v149 offset:20480
	ds_read_b128 v[194:197], v149 offset:21504
	ds_read_b128 v[212:215], v149 offset:22528
	ds_read_b128 v[216:219], v149 offset:23552
	global_load_lds_dwordx4 v[220:221], off
	s_add_i32 m0, s0, 0x2000
	s_add_u32 s0, s36, 0x80000
	v_lshl_add_u64 v[222:223], s[36:37], 0, v[128:129]
	s_addc_u32 s1, s37, 0
	s_add_i32 s59, s63, s40
	global_load_lds_dwordx4 v[222:223], off
	v_lshl_add_u64 v[224:225], s[0:1], 0, v[198:199]
	s_mov_b32 m0, s59
	v_lshl_add_u64 v[226:227], s[38:39], 0, v[130:131]
	global_load_lds_dwordx4 v[224:225], off
	v_lshl_add_u64 v[224:225], s[0:1], 0, v[128:129]
	s_add_i32 m0, s59, 0x2000
	s_nop 0
	global_load_lds_dwordx4 v[224:225], off
	v_lshl_add_u64 v[224:225], s[38:39], 0, v[132:133]
	s_mov_b32 m0, s42
	s_nop 0
	global_load_lds_dwordx4 v[224:225], off
	s_mov_b32 m0, s43
	s_nop 0
	global_load_lds_dwordx4 v[226:227], off
	s_waitcnt vmcnt(63)
	s_waitcnt lgkmcnt(0)
	s_barrier
	s_setprio 1
	s_waitcnt lgkmcnt(0)
	v_mfma_f32_16x16x32_bf16 v[56:59], v[138:141], v[174:177], 0
	v_mfma_f32_16x16x32_bf16 v[48:51], v[150:153], v[174:177], 0
	v_mfma_f32_16x16x32_bf16 v[40:43], v[138:141], v[182:185], 0
	v_mfma_f32_16x16x32_bf16 v[32:35], v[150:153], v[182:185], 0
	v_mfma_f32_16x16x32_bf16 v[24:27], v[138:141], v[190:193], 0
	v_mfma_f32_16x16x32_bf16 v[16:19], v[150:153], v[190:193], 0
	v_mfma_f32_16x16x32_bf16 v[8:11], v[138:141], v[212:215], 0
	v_mfma_f32_16x16x32_bf16 v[0:3], v[150:153], v[212:215], 0
	v_mfma_f32_16x16x32_bf16 v[56:59], v[142:145], v[178:181], v[56:59]
	v_mfma_f32_16x16x32_bf16 v[48:51], v[154:157], v[178:181], v[48:51]
	v_mfma_f32_16x16x32_bf16 v[40:43], v[142:145], v[186:189], v[40:43]
	v_mfma_f32_16x16x32_bf16 v[32:35], v[154:157], v[186:189], v[32:35]
	v_mfma_f32_16x16x32_bf16 v[24:27], v[142:145], v[194:197], v[24:27]
	v_mfma_f32_16x16x32_bf16 v[16:19], v[154:157], v[194:197], v[16:19]
	v_mfma_f32_16x16x32_bf16 v[8:11], v[142:145], v[216:219], v[8:11]
	v_mfma_f32_16x16x32_bf16 v[0:3], v[154:157], v[216:219], v[0:3]
	s_setprio 0
	s_setprio 1
	v_mfma_f32_16x16x32_bf16 v[60:63], v[158:161], v[174:177], 0
	v_mfma_f32_16x16x32_bf16 v[52:55], v[166:169], v[174:177], 0
	v_mfma_f32_16x16x32_bf16 v[44:47], v[158:161], v[182:185], 0
	v_mfma_f32_16x16x32_bf16 v[36:39], v[166:169], v[182:185], 0
	v_mfma_f32_16x16x32_bf16 v[28:31], v[158:161], v[190:193], 0
	v_mfma_f32_16x16x32_bf16 v[20:23], v[166:169], v[190:193], 0
	v_mfma_f32_16x16x32_bf16 v[12:15], v[158:161], v[212:215], 0
	v_mfma_f32_16x16x32_bf16 v[4:7], v[166:169], v[212:215], 0
	v_mfma_f32_16x16x32_bf16 v[60:63], v[162:165], v[178:181], v[60:63]
	v_mfma_f32_16x16x32_bf16 v[52:55], v[170:173], v[178:181], v[52:55]
	v_mfma_f32_16x16x32_bf16 v[44:47], v[162:165], v[186:189], v[44:47]
	v_mfma_f32_16x16x32_bf16 v[36:39], v[170:173], v[186:189], v[36:39]
	v_mfma_f32_16x16x32_bf16 v[28:31], v[162:165], v[194:197], v[28:31]
	v_mfma_f32_16x16x32_bf16 v[20:23], v[170:173], v[194:197], v[20:23]
	v_mfma_f32_16x16x32_bf16 v[12:15], v[162:165], v[216:219], v[12:15]
	v_mfma_f32_16x16x32_bf16 v[4:7], v[170:173], v[216:219], v[4:7]
	s_setprio 0
	s_barrier
	s_add_i32 s59, 0, 0x18000
	s_add_i32 s63, 0, 0x1c000
	v_add_u32_e32 v154, s59, v147
	v_add_u32_e32 v170, s63, v147
	ds_read_b128 v[138:141], v154
	ds_read_b128 v[142:145], v154 offset:1024
	ds_read_b128 v[150:153], v154 offset:2048
	ds_read_b128 v[154:157], v154 offset:3072
	ds_read_b128 v[158:161], v170
	ds_read_b128 v[162:165], v170 offset:1024
	ds_read_b128 v[166:169], v170 offset:2048
	ds_read_b128 v[170:173], v170 offset:3072
	s_add_u32 s0, s38, 0x80000
	s_addc_u32 s1, s39, 0
	s_mov_b32 m0, s44
	v_lshl_add_u64 v[228:229], s[0:1], 0, v[132:133]
	ds_read_b128 v[174:177], v149 offset:32768
	ds_read_b128 v[178:181], v149 offset:33792
	ds_read_b128 v[182:185], v149 offset:34816
	ds_read_b128 v[186:189], v149 offset:35840
	ds_read_b128 v[190:193], v149 offset:36864
	ds_read_b128 v[194:197], v149 offset:37888
	ds_read_b128 v[212:215], v149 offset:38912
	ds_read_b128 v[216:219], v149 offset:39936
	global_load_lds_dwordx4 v[228:229], off
	v_lshl_add_u64 v[228:229], s[0:1], 0, v[130:131]
	s_mov_b32 m0, s45
	s_nop 0
	global_load_lds_dwordx4 v[228:229], off
	s_waitcnt vmcnt(8)
	s_waitcnt lgkmcnt(0)
	s_barrier
	s_setprio 1
	s_waitcnt lgkmcnt(0)
	v_mfma_f32_16x16x32_bf16 v[124:127], v[138:141], v[174:177], v[124:127]
	v_mfma_f32_16x16x32_bf16 v[116:119], v[150:153], v[174:177], v[116:119]
	v_mfma_f32_16x16x32_bf16 v[108:111], v[138:141], v[182:185], v[108:111]
	v_mfma_f32_16x16x32_bf16 v[96:99], v[150:153], v[182:185], v[96:99]
	v_mfma_f32_16x16x32_bf16 v[88:91], v[138:141], v[190:193], v[88:91]
	v_mfma_f32_16x16x32_bf16 v[80:83], v[150:153], v[190:193], v[80:83]
	v_mfma_f32_16x16x32_bf16 v[72:75], v[138:141], v[212:215], v[72:75]
	v_mfma_f32_16x16x32_bf16 v[64:67], v[150:153], v[212:215], v[64:67]
	v_mfma_f32_16x16x32_bf16 v[124:127], v[142:145], v[178:181], v[124:127]
	v_mfma_f32_16x16x32_bf16 v[116:119], v[154:157], v[178:181], v[116:119]
	v_mfma_f32_16x16x32_bf16 v[108:111], v[142:145], v[186:189], v[108:111]
	v_mfma_f32_16x16x32_bf16 v[96:99], v[154:157], v[186:189], v[96:99]
	v_mfma_f32_16x16x32_bf16 v[88:91], v[142:145], v[194:197], v[88:91]
	v_mfma_f32_16x16x32_bf16 v[80:83], v[154:157], v[194:197], v[80:83]
	v_mfma_f32_16x16x32_bf16 v[72:75], v[142:145], v[216:219], v[72:75]
	v_mfma_f32_16x16x32_bf16 v[64:67], v[154:157], v[216:219], v[64:67]
	s_setprio 0
	s_setprio 1
	v_mfma_f32_16x16x32_bf16 v[120:123], v[158:161], v[174:177], v[120:123]
	v_mfma_f32_16x16x32_bf16 v[112:115], v[166:169], v[174:177], v[112:115]
	v_mfma_f32_16x16x32_bf16 v[104:107], v[158:161], v[182:185], v[104:107]
	v_mfma_f32_16x16x32_bf16 v[100:103], v[166:169], v[182:185], v[100:103]
	v_mfma_f32_16x16x32_bf16 v[92:95], v[158:161], v[190:193], v[92:95]
	v_mfma_f32_16x16x32_bf16 v[84:87], v[166:169], v[190:193], v[84:87]
	v_mfma_f32_16x16x32_bf16 v[76:79], v[158:161], v[212:215], v[76:79]
	v_mfma_f32_16x16x32_bf16 v[68:71], v[166:169], v[212:215], v[68:71]
	v_mfma_f32_16x16x32_bf16 v[120:123], v[162:165], v[178:181], v[120:123]
	v_mfma_f32_16x16x32_bf16 v[112:115], v[170:173], v[178:181], v[112:115]
	v_mfma_f32_16x16x32_bf16 v[104:107], v[162:165], v[186:189], v[104:107]
	v_mfma_f32_16x16x32_bf16 v[100:103], v[170:173], v[186:189], v[100:103]
	v_mfma_f32_16x16x32_bf16 v[92:95], v[162:165], v[194:197], v[92:95]
	v_mfma_f32_16x16x32_bf16 v[84:87], v[170:173], v[194:197], v[84:87]
	v_mfma_f32_16x16x32_bf16 v[76:79], v[162:165], v[216:219], v[76:79]
	v_mfma_f32_16x16x32_bf16 v[68:71], v[170:173], v[216:219], v[68:71]
	s_setprio 0
	s_barrier
	s_add_i32 s0, s59, s40
	v_lshl_add_u64 v[220:221], v[220:221], 0, s[54:55]
	s_mov_b32 m0, s0
	ds_read_b128 v[174:177], v149 offset:49152
	ds_read_b128 v[178:181], v149 offset:50176
	ds_read_b128 v[182:185], v149 offset:51200
	ds_read_b128 v[186:189], v149 offset:52224
	ds_read_b128 v[190:193], v149 offset:53248
	ds_read_b128 v[194:197], v149 offset:54272
	ds_read_b128 v[212:215], v149 offset:55296
	ds_read_b128 v[216:219], v149 offset:56320
	global_load_lds_dwordx4 v[220:221], off
	s_add_i32 m0, s0, 0x2000
	s_add_u32 s0, s36, 0x80080
	v_lshl_add_u64 v[220:221], v[222:223], 0, s[54:55]
	s_addc_u32 s1, s37, 0
	s_add_i32 s36, s63, s40
	global_load_lds_dwordx4 v[220:221], off
	v_lshl_add_u64 v[220:221], s[0:1], 0, v[198:199]
	s_mov_b32 m0, s36
	s_nop 0
	global_load_lds_dwordx4 v[220:221], off
	v_lshl_add_u64 v[220:221], s[0:1], 0, v[128:129]
	s_add_i32 m0, s36, 0x2000
	s_nop 0
	global_load_lds_dwordx4 v[220:221], off
	v_lshl_add_u64 v[220:221], v[224:225], 0, s[54:55]
	s_mov_b32 m0, s47
	s_nop 0
	global_load_lds_dwordx4 v[220:221], off
	v_lshl_add_u64 v[220:221], v[226:227], 0, s[54:55]
	s_mov_b32 m0, s48
	s_nop 0
	global_load_lds_dwordx4 v[220:221], off
	s_waitcnt vmcnt(8)
	s_waitcnt lgkmcnt(0)
	s_barrier
	s_setprio 1
	s_waitcnt lgkmcnt(0)
	v_mfma_f32_16x16x32_bf16 v[56:59], v[138:141], v[174:177], v[56:59]
	v_mfma_f32_16x16x32_bf16 v[48:51], v[150:153], v[174:177], v[48:51]
	v_mfma_f32_16x16x32_bf16 v[40:43], v[138:141], v[182:185], v[40:43]
	v_mfma_f32_16x16x32_bf16 v[32:35], v[150:153], v[182:185], v[32:35]
	v_mfma_f32_16x16x32_bf16 v[24:27], v[138:141], v[190:193], v[24:27]
	v_mfma_f32_16x16x32_bf16 v[16:19], v[150:153], v[190:193], v[16:19]
	v_mfma_f32_16x16x32_bf16 v[8:11], v[138:141], v[212:215], v[8:11]
	v_mfma_f32_16x16x32_bf16 v[0:3], v[150:153], v[212:215], v[0:3]
	v_mfma_f32_16x16x32_bf16 v[56:59], v[142:145], v[178:181], v[56:59]
	v_mfma_f32_16x16x32_bf16 v[48:51], v[154:157], v[178:181], v[48:51]
	v_mfma_f32_16x16x32_bf16 v[40:43], v[142:145], v[186:189], v[40:43]
	v_mfma_f32_16x16x32_bf16 v[32:35], v[154:157], v[186:189], v[32:35]
	v_mfma_f32_16x16x32_bf16 v[24:27], v[142:145], v[194:197], v[24:27]
	v_mfma_f32_16x16x32_bf16 v[16:19], v[154:157], v[194:197], v[16:19]
	v_mfma_f32_16x16x32_bf16 v[8:11], v[142:145], v[216:219], v[8:11]
	v_mfma_f32_16x16x32_bf16 v[0:3], v[154:157], v[216:219], v[0:3]
	s_setprio 0
	s_setprio 1
	v_mfma_f32_16x16x32_bf16 v[60:63], v[158:161], v[174:177], v[60:63]
	v_mfma_f32_16x16x32_bf16 v[52:55], v[166:169], v[174:177], v[52:55]
	v_mfma_f32_16x16x32_bf16 v[44:47], v[158:161], v[182:185], v[44:47]
	v_mfma_f32_16x16x32_bf16 v[36:39], v[166:169], v[182:185], v[36:39]
	v_mfma_f32_16x16x32_bf16 v[28:31], v[158:161], v[190:193], v[28:31]
	v_mfma_f32_16x16x32_bf16 v[20:23], v[166:169], v[190:193], v[20:23]
	v_mfma_f32_16x16x32_bf16 v[12:15], v[158:161], v[212:215], v[12:15]
	v_mfma_f32_16x16x32_bf16 v[4:7], v[166:169], v[212:215], v[4:7]
	v_mfma_f32_16x16x32_bf16 v[60:63], v[162:165], v[178:181], v[60:63]
	v_mfma_f32_16x16x32_bf16 v[52:55], v[170:173], v[178:181], v[52:55]
	v_mfma_f32_16x16x32_bf16 v[44:47], v[162:165], v[186:189], v[44:47]
	v_mfma_f32_16x16x32_bf16 v[36:39], v[170:173], v[186:189], v[36:39]
	v_mfma_f32_16x16x32_bf16 v[28:31], v[162:165], v[194:197], v[28:31]
	v_mfma_f32_16x16x32_bf16 v[20:23], v[170:173], v[194:197], v[20:23]
	v_mfma_f32_16x16x32_bf16 v[12:15], v[162:165], v[216:219], v[12:15]
	v_mfma_f32_16x16x32_bf16 v[4:7], v[170:173], v[216:219], v[4:7]
	s_setprio 0
	s_barrier
	s_add_i32 s61, s61, 2
	s_add_u32 s30, s30, 0x100
	s_addc_u32 s31, s31, 0
	s_add_u32 s35, s35, 0x100
	s_addc_u32 s52, s52, 0
